# epilogue residual loads (DOWN, OUT, DOWN tail, POST GEMM) issued as one batch per 8-row group with counted vmcnt instead of load-wait-store chains
# speedup vs baseline: 1.0470x; 1.0028x over previous
; DI unsigned pack2(float a, float b) { fl2_t f; f.x = a; f.y = b; bf16x2_t r = __builtin_convertvector(f, bf16x2_t); return __builtin_bit_cast(unsigned, r); }
; DI float bflo(unsigned u) { return __uint_as_float(u << 16); }
; DI float bfhi(unsigned u) { return __uint_as_float(u & 0xffff0000u); }
; DI float sigmoidf_(float x) { return __builtin_amdgcn_rcpf(1.f + __expf(-x)); }
; DI void store4(u16* dst, float a, float b, float c, float d) { *(uint2*)dst = make_uint2(pack2(a, b), pack2(c, d)); }
;     ...
;   const int nw = n0 + wn * 64;
; #pragma unroll
;   for (int i = 0; i < MI; ++i) {
;     const int m = m0 + wm * (MI * 32) + i * 32 + l32;
;     if (EPI == EPI_UP) {
;       const float rs = rsl[m - m0];
;       const int hb0 = nw >> 1;
; #pragma unroll
;       for (int gq = 0; gq < 4; ++gq) {
;         float v[4];
; #pragma unroll
;         for (int r = 0; r < 4; ++r) {
;           float gt = acc[i][0][4 * gq + r] * rs, up = acc[i][1][4 * gq + r] * rs;
;           v[r] = gt * sigmoidf_(gt) * up;
;         }
;         int hid = hb0 + 8 * gq + 4 * hh;
;         u16* dst = hid < 1408 ? p.regB + (size_t)m * 1408 + hid : (u16*)p.out + (size_t)m * 1408 + (hid - 1408);
;         store4(dst, v[0], v[1], v[2], v[3]);
;       }
;     } else if (EPI == EPI_RES) {
;       float ss = 0.f;
; #pragma unroll
;       for (int j = 0; j < 2; ++j)
; #pragma unroll
;         for (int gq = 0; gq < 4; ++gq) {
;           u16* hp = p.hb + (size_t)m * 1024 + nw + j * 32 + 8 * gq + 4 * hh;
;           uint2 old = *(const uint2*)hp;
;           float h0 = bflo(old.x) + g.scale * acc[i][j][4 * gq + 0];
;           float h1 = bfhi(old.x) + g.scale * acc[i][j][4 * gq + 1];
;           float h2 = bflo(old.y) + g.scale * acc[i][j][4 * gq + 2];
;           float h3 = bfhi(old.y) + g.scale * acc[i][j][4 * gq + 3];
;           unsigned p0 = pack2(h0, h1), p1 = pack2(h2, h3);
;           *(uint2*)hp = make_uint2(p0, p1);
;           float r0 = bflo(p0), r1 = bfhi(p0), r2 = bflo(p1), r3 = bfhi(p1);
;           ss += r0 * r0 + r1 * r1 + r2 * r2 + r3 * r3;
;         }
;       ss += __shfl_xor(ss, 32);
;       if (hh == 0) p.ssq[(size_t)(nw >> 6) * TP + m] = ss;
.LBB0_49:
	v_lshl_add_u32 v134, v201, 6, s55
	v_lshl_add_u32 v0, v199, 7, s54
	v_ashrrev_i32_e32 v135, 31, v134
	v_or_b32_e32 v130, v0, v200
	v_lshl_add_u64 v[132:133], v[134:135], 1, s[44:45]
	v_lshlrev_b32_e32 v0, 3, v178
	v_and_b32_e32 v131, 64, v183
	v_lshl_add_u64 v[132:133], v[132:133], 0, v[0:1]
	v_xor_b32_e32 v0, 32, v183
	v_add_u32_e32 v131, 64, v131
	v_cmp_lt_i32_e32 vcc, v0, v131
	v_lshrrev_b32_e32 v131, 6, v134
	s_mov_b32 s2, 0x20400
	v_mul_lo_u32 v134, v131, s2
	v_ashrrev_i32_e32 v131, 31, v130
	v_lshlrev_b64 v[136:137], 11, v[130:131]
	v_lshl_add_u64 v[136:137], v[132:133], 0, v[136:137]
	s_barrier
	global_load_dwordx2 v[216:217], v[136:137], off
	global_load_dwordx2 v[218:219], v[136:137], off offset:16
	global_load_dwordx2 v[220:221], v[136:137], off offset:32
	global_load_dwordx2 v[222:223], v[136:137], off offset:48
	global_load_dwordx2 v[224:225], v[136:137], off offset:64
	global_load_dwordx2 v[226:227], v[136:137], off offset:80
	global_load_dwordx2 v[228:229], v[136:137], off offset:96
	global_load_dwordx2 v[230:231], v[136:137], off offset:112
	v_cndmask_b32_e32 v0, v183, v0, vcc
	v_lshlrev_b32_e32 v0, 2, v0
	v_ashrrev_i32_e32 v135, 31, v134
	v_lshl_add_u64 v[134:135], s[42:43], 0, v[134:135]
	v_cmp_gt_u32_e32 vcc, 32, v170
	s_waitcnt vmcnt(7)
	v_lshlrev_b32_e32 v140, 16, v216
	v_and_b32_e32 v141, 0xffff0000, v216
	v_lshlrev_b32_e32 v138, 16, v217
	v_and_b32_e32 v139, 0xffff0000, v217
	v_pk_add_f32 v[114:115], v[114:115], v[140:141]
	v_pk_add_f32 v[116:117], v[116:117], v[138:139]
	v_cvt_pk_bf16_f32 v114, v114, v115
	v_cvt_pk_bf16_f32 v115, v116, v117
	global_store_dwordx2 v[136:137], v[114:115], off
	v_lshlrev_b32_e32 v116, 16, v114
	v_and_b32_e32 v114, 0xffff0000, v114
	v_mul_f32_e32 v138, v114, v114
	v_lshlrev_b32_e32 v117, 16, v115
	v_fmac_f32_e32 v138, v116, v116
	v_and_b32_e32 v115, 0xffff0000, v115
	v_fmac_f32_e32 v138, v117, v117
	v_fmac_f32_e32 v138, v115, v115
	s_waitcnt vmcnt(7)
	v_lshlrev_b32_e32 v116, 16, v218
	v_and_b32_e32 v117, 0xffff0000, v218
	v_pk_add_f32 v[116:117], v[118:119], v[116:117]
	v_lshlrev_b32_e32 v114, 16, v219
	v_and_b32_e32 v115, 0xffff0000, v219
	v_pk_add_f32 v[114:115], v[120:121], v[114:115]
	v_cvt_pk_bf16_f32 v116, v116, v117
	v_cvt_pk_bf16_f32 v117, v114, v115
	v_and_b32_e32 v115, 0xffff0000, v116
	v_lshlrev_b32_e32 v114, 16, v116
	v_mul_f32_e32 v115, v115, v115
	global_store_dwordx2 v[136:137], v[116:117], off offset:16
	v_lshlrev_b32_e32 v116, 16, v117
	v_fmac_f32_e32 v115, v114, v114
	v_and_b32_e32 v117, 0xffff0000, v117
	v_fmac_f32_e32 v115, v116, v116
	v_fmac_f32_e32 v115, v117, v117
	v_add_f32_e32 v118, v138, v115
	s_waitcnt vmcnt(7)
	v_lshlrev_b32_e32 v116, 16, v220
	v_and_b32_e32 v117, 0xffff0000, v220
	v_pk_add_f32 v[116:117], v[122:123], v[116:117]
	v_lshlrev_b32_e32 v114, 16, v221
	v_and_b32_e32 v115, 0xffff0000, v221
	v_pk_add_f32 v[114:115], v[124:125], v[114:115]
	v_cvt_pk_bf16_f32 v116, v116, v117
	v_cvt_pk_bf16_f32 v117, v114, v115
	v_and_b32_e32 v115, 0xffff0000, v116
	v_lshlrev_b32_e32 v114, 16, v116
	v_mul_f32_e32 v115, v115, v115
	global_store_dwordx2 v[136:137], v[116:117], off offset:32
	v_lshlrev_b32_e32 v116, 16, v117
	v_fmac_f32_e32 v115, v114, v114
	v_and_b32_e32 v117, 0xffff0000, v117
	v_fmac_f32_e32 v115, v116, v116
	v_fmac_f32_e32 v115, v117, v117
	v_add_f32_e32 v118, v118, v115
	s_waitcnt vmcnt(7)
	v_lshlrev_b32_e32 v116, 16, v222
	v_and_b32_e32 v117, 0xffff0000, v222
	v_pk_add_f32 v[116:117], v[126:127], v[116:117]
	v_lshlrev_b32_e32 v114, 16, v223
	v_and_b32_e32 v115, 0xffff0000, v223
	v_pk_add_f32 v[114:115], v[128:129], v[114:115]
	v_cvt_pk_bf16_f32 v116, v116, v117
	v_cvt_pk_bf16_f32 v117, v114, v115
	v_and_b32_e32 v115, 0xffff0000, v116
	v_lshlrev_b32_e32 v114, 16, v116
	v_mul_f32_e32 v115, v115, v115
	global_store_dwordx2 v[136:137], v[116:117], off offset:48
	v_lshlrev_b32_e32 v116, 16, v117
	v_fmac_f32_e32 v115, v114, v114
	v_and_b32_e32 v117, 0xffff0000, v117
	v_fmac_f32_e32 v115, v116, v116
	v_fmac_f32_e32 v115, v117, v117
	v_add_f32_e32 v118, v118, v115
	s_waitcnt vmcnt(7)
	v_lshlrev_b32_e32 v116, 16, v224
	v_and_b32_e32 v117, 0xffff0000, v224
	v_lshlrev_b32_e32 v114, 16, v225
	v_and_b32_e32 v115, 0xffff0000, v225
	v_pk_add_f32 v[98:99], v[98:99], v[116:117]
	v_pk_add_f32 v[100:101], v[100:101], v[114:115]
	v_cvt_pk_bf16_f32 v98, v98, v99
	v_cvt_pk_bf16_f32 v99, v100, v101
	global_store_dwordx2 v[136:137], v[98:99], off offset:64
	v_lshlrev_b32_e32 v100, 16, v98
	v_and_b32_e32 v98, 0xffff0000, v98
	v_mul_f32_e32 v98, v98, v98
	v_lshlrev_b32_e32 v101, 16, v99
	v_fmac_f32_e32 v98, v100, v100
	v_and_b32_e32 v99, 0xffff0000, v99
	v_fmac_f32_e32 v98, v101, v101
	v_fmac_f32_e32 v98, v99, v99
	v_add_f32_e32 v114, v118, v98
	s_waitcnt vmcnt(7)
	v_lshlrev_b32_e32 v100, 16, v226
	v_and_b32_e32 v101, 0xffff0000, v226
	v_pk_add_f32 v[100:101], v[102:103], v[100:101]
	v_lshlrev_b32_e32 v98, 16, v227
	v_and_b32_e32 v99, 0xffff0000, v227
	v_pk_add_f32 v[98:99], v[104:105], v[98:99]
	v_cvt_pk_bf16_f32 v100, v100, v101
	v_cvt_pk_bf16_f32 v101, v98, v99
	v_and_b32_e32 v99, 0xffff0000, v100
	v_lshlrev_b32_e32 v98, 16, v100
	v_mul_f32_e32 v99, v99, v99
	global_store_dwordx2 v[136:137], v[100:101], off offset:80
	v_lshlrev_b32_e32 v100, 16, v101
	v_fmac_f32_e32 v99, v98, v98
	v_and_b32_e32 v101, 0xffff0000, v101
	v_fmac_f32_e32 v99, v100, v100
	v_fmac_f32_e32 v99, v101, v101
	v_add_f32_e32 v102, v114, v99
	s_waitcnt vmcnt(7)
	v_lshlrev_b32_e32 v100, 16, v228
	v_and_b32_e32 v101, 0xffff0000, v228
	v_pk_add_f32 v[100:101], v[106:107], v[100:101]
	v_lshlrev_b32_e32 v98, 16, v229
	v_and_b32_e32 v99, 0xffff0000, v229
	v_pk_add_f32 v[98:99], v[108:109], v[98:99]
	v_cvt_pk_bf16_f32 v100, v100, v101
	v_cvt_pk_bf16_f32 v101, v98, v99
	v_and_b32_e32 v99, 0xffff0000, v100
	v_lshlrev_b32_e32 v98, 16, v100
	v_mul_f32_e32 v99, v99, v99
	global_store_dwordx2 v[136:137], v[100:101], off offset:96
	v_lshlrev_b32_e32 v100, 16, v101
	v_fmac_f32_e32 v99, v98, v98
	v_and_b32_e32 v101, 0xffff0000, v101
	v_fmac_f32_e32 v99, v100, v100
	v_fmac_f32_e32 v99, v101, v101
	v_add_f32_e32 v100, v102, v99
	s_waitcnt vmcnt(7)
	v_lshlrev_b32_e32 v102, 16, v230
	v_and_b32_e32 v103, 0xffff0000, v230
	v_pk_add_f32 v[102:103], v[110:111], v[102:103]
	v_lshlrev_b32_e32 v98, 16, v231
	v_and_b32_e32 v99, 0xffff0000, v231
	v_pk_add_f32 v[98:99], v[112:113], v[98:99]
	v_cvt_pk_bf16_f32 v102, v102, v103
	v_cvt_pk_bf16_f32 v103, v98, v99
	v_and_b32_e32 v99, 0xffff0000, v102
	v_lshlrev_b32_e32 v98, 16, v102
	v_mul_f32_e32 v99, v99, v99
	v_lshlrev_b32_e32 v101, 16, v103
	v_fmac_f32_e32 v99, v98, v98
	global_store_dwordx2 v[136:137], v[102:103], off offset:112
	v_and_b32_e32 v102, 0xffff0000, v103
	v_fmac_f32_e32 v99, v101, v101
	v_fmac_f32_e32 v99, v102, v102
	v_add_f32_e32 v100, v100, v99
	ds_bpermute_b32 v101, v0, v100
	v_lshl_add_u64 v[98:99], v[130:131], 2, v[134:135]
	s_and_saveexec_b64 s[2:3], vcc
	s_cbranch_execz .LBB0_51
	s_waitcnt lgkmcnt(0)
	v_add_f32_e32 v100, v100, v101
	global_store_dword v[98:99], v100, off
; DI unsigned pack2(float a, float b) { fl2_t f; f.x = a; f.y = b; bf16x2_t r = __builtin_convertvector(f, bf16x2_t); return __builtin_bit_cast(unsigned, r); }
; DI float bflo(unsigned u) { return __uint_as_float(u << 16); }
; DI float bfhi(unsigned u) { return __uint_as_float(u & 0xffff0000u); }
;     ...
;     } else if (EPI == EPI_RES) {
;       float ss = 0.f;
; #pragma unroll
;       for (int j = 0; j < 2; ++j)
; #pragma unroll
;         for (int gq = 0; gq < 4; ++gq) {
;           u16* hp = p.hb + (size_t)m * 1024 + nw + j * 32 + 8 * gq + 4 * hh;
;           uint2 old = *(const uint2*)hp;
;           float h0 = bflo(old.x) + g.scale * acc[i][j][4 * gq + 0];
;           float h1 = bfhi(old.x) + g.scale * acc[i][j][4 * gq + 1];
;           float h2 = bflo(old.y) + g.scale * acc[i][j][4 * gq + 2];
;           float h3 = bfhi(old.y) + g.scale * acc[i][j][4 * gq + 3];
;           unsigned p0 = pack2(h0, h1), p1 = pack2(h2, h3);
;           *(uint2*)hp = make_uint2(p0, p1);
;           float r0 = bflo(p0), r1 = bfhi(p0), r2 = bflo(p1), r3 = bfhi(p1);
;           ss += r0 * r0 + r1 * r1 + r2 * r2 + r3 * r3;
;         }
;       ss += __shfl_xor(ss, 32);
;       if (hh == 0) p.ssq[(size_t)(nw >> 6) * TP + m] = ss;
.LBB0_51:
	s_or_b64 exec, exec, s[2:3]
	v_or_b32_e32 v100, 32, v130
	s_waitcnt lgkmcnt(0)
	v_ashrrev_i32_e32 v101, 31, v100
	v_lshlrev_b64 v[100:101], 11, v[100:101]
	v_lshl_add_u64 v[100:101], v[132:133], 0, v[100:101]
	global_load_dwordx2 v[216:217], v[100:101], off
	global_load_dwordx2 v[218:219], v[100:101], off offset:16
	global_load_dwordx2 v[220:221], v[100:101], off offset:32
	global_load_dwordx2 v[222:223], v[100:101], off offset:48
	global_load_dwordx2 v[224:225], v[100:101], off offset:64
	global_load_dwordx2 v[226:227], v[100:101], off offset:80
	global_load_dwordx2 v[228:229], v[100:101], off offset:96
	global_load_dwordx2 v[230:231], v[100:101], off offset:112
	s_waitcnt vmcnt(7)
	v_lshlrev_b32_e32 v104, 16, v216
	v_and_b32_e32 v105, 0xffff0000, v216
	v_lshlrev_b32_e32 v102, 16, v217
	v_and_b32_e32 v103, 0xffff0000, v217
	v_pk_add_f32 v[82:83], v[82:83], v[104:105]
	v_pk_add_f32 v[84:85], v[84:85], v[102:103]
	v_cvt_pk_bf16_f32 v82, v82, v83
	v_cvt_pk_bf16_f32 v83, v84, v85
	global_store_dwordx2 v[100:101], v[82:83], off
	v_lshlrev_b32_e32 v84, 16, v82
	v_and_b32_e32 v82, 0xffff0000, v82
	v_mul_f32_e32 v102, v82, v82
	v_lshlrev_b32_e32 v85, 16, v83
	v_fmac_f32_e32 v102, v84, v84
	v_and_b32_e32 v83, 0xffff0000, v83
	v_fmac_f32_e32 v102, v85, v85
	v_fmac_f32_e32 v102, v83, v83
	s_waitcnt vmcnt(7)
	v_lshlrev_b32_e32 v84, 16, v218
	v_and_b32_e32 v85, 0xffff0000, v218
	v_pk_add_f32 v[84:85], v[86:87], v[84:85]
	v_lshlrev_b32_e32 v82, 16, v219
	v_and_b32_e32 v83, 0xffff0000, v219
	v_pk_add_f32 v[82:83], v[88:89], v[82:83]
	v_cvt_pk_bf16_f32 v84, v84, v85
	v_cvt_pk_bf16_f32 v85, v82, v83
	v_and_b32_e32 v83, 0xffff0000, v84
	v_lshlrev_b32_e32 v82, 16, v84
	v_mul_f32_e32 v83, v83, v83
	global_store_dwordx2 v[100:101], v[84:85], off offset:16
	v_lshlrev_b32_e32 v84, 16, v85
	v_fmac_f32_e32 v83, v82, v82
	v_and_b32_e32 v85, 0xffff0000, v85
	v_fmac_f32_e32 v83, v84, v84
	v_fmac_f32_e32 v83, v85, v85
	v_add_f32_e32 v86, v102, v83
	s_waitcnt vmcnt(7)
	v_lshlrev_b32_e32 v84, 16, v220
	v_and_b32_e32 v85, 0xffff0000, v220
	v_pk_add_f32 v[84:85], v[90:91], v[84:85]
	v_lshlrev_b32_e32 v82, 16, v221
	v_and_b32_e32 v83, 0xffff0000, v221
	v_pk_add_f32 v[82:83], v[92:93], v[82:83]
	v_cvt_pk_bf16_f32 v84, v84, v85
	v_cvt_pk_bf16_f32 v85, v82, v83
	v_and_b32_e32 v83, 0xffff0000, v84
	v_lshlrev_b32_e32 v82, 16, v84
	v_mul_f32_e32 v83, v83, v83
	global_store_dwordx2 v[100:101], v[84:85], off offset:32
	v_lshlrev_b32_e32 v84, 16, v85
	v_fmac_f32_e32 v83, v82, v82
	v_and_b32_e32 v85, 0xffff0000, v85
	v_fmac_f32_e32 v83, v84, v84
	v_fmac_f32_e32 v83, v85, v85
	v_add_f32_e32 v86, v86, v83
	s_waitcnt vmcnt(7)
	v_lshlrev_b32_e32 v84, 16, v222
	v_and_b32_e32 v85, 0xffff0000, v222
	v_pk_add_f32 v[84:85], v[94:95], v[84:85]
	v_lshlrev_b32_e32 v82, 16, v223
	v_and_b32_e32 v83, 0xffff0000, v223
	v_pk_add_f32 v[82:83], v[96:97], v[82:83]
	v_cvt_pk_bf16_f32 v84, v84, v85
	v_cvt_pk_bf16_f32 v85, v82, v83
	v_and_b32_e32 v83, 0xffff0000, v84
	v_lshlrev_b32_e32 v82, 16, v84
	v_mul_f32_e32 v83, v83, v83
	global_store_dwordx2 v[100:101], v[84:85], off offset:48
	v_lshlrev_b32_e32 v84, 16, v85
	v_fmac_f32_e32 v83, v82, v82
	v_and_b32_e32 v85, 0xffff0000, v85
	v_fmac_f32_e32 v83, v84, v84
	v_fmac_f32_e32 v83, v85, v85
	v_add_f32_e32 v86, v86, v83
	s_waitcnt vmcnt(7)
	v_lshlrev_b32_e32 v84, 16, v224
	v_and_b32_e32 v85, 0xffff0000, v224
	v_lshlrev_b32_e32 v82, 16, v225
	v_and_b32_e32 v83, 0xffff0000, v225
	v_pk_add_f32 v[66:67], v[66:67], v[84:85]
	v_pk_add_f32 v[68:69], v[68:69], v[82:83]
	v_cvt_pk_bf16_f32 v66, v66, v67
	v_cvt_pk_bf16_f32 v67, v68, v69
	global_store_dwordx2 v[100:101], v[66:67], off offset:64
	v_lshlrev_b32_e32 v68, 16, v66
	v_and_b32_e32 v66, 0xffff0000, v66
	v_mul_f32_e32 v66, v66, v66
	v_lshlrev_b32_e32 v69, 16, v67
	v_fmac_f32_e32 v66, v68, v68
	v_and_b32_e32 v67, 0xffff0000, v67
	v_fmac_f32_e32 v66, v69, v69
	v_fmac_f32_e32 v66, v67, v67
	v_add_f32_e32 v82, v86, v66
	s_waitcnt vmcnt(7)
	v_lshlrev_b32_e32 v68, 16, v226
	v_and_b32_e32 v69, 0xffff0000, v226
	v_pk_add_f32 v[68:69], v[70:71], v[68:69]
	v_lshlrev_b32_e32 v66, 16, v227
	v_and_b32_e32 v67, 0xffff0000, v227
	v_pk_add_f32 v[66:67], v[72:73], v[66:67]
	v_cvt_pk_bf16_f32 v68, v68, v69
	v_cvt_pk_bf16_f32 v69, v66, v67
	v_and_b32_e32 v67, 0xffff0000, v68
	v_lshlrev_b32_e32 v66, 16, v68
	v_mul_f32_e32 v67, v67, v67
	global_store_dwordx2 v[100:101], v[68:69], off offset:80
	v_lshlrev_b32_e32 v68, 16, v69
	v_fmac_f32_e32 v67, v66, v66
	v_and_b32_e32 v69, 0xffff0000, v69
	v_fmac_f32_e32 v67, v68, v68
	v_fmac_f32_e32 v67, v69, v69
	v_add_f32_e32 v70, v82, v67
	s_waitcnt vmcnt(7)
	v_lshlrev_b32_e32 v68, 16, v228
	v_and_b32_e32 v69, 0xffff0000, v228
	v_pk_add_f32 v[68:69], v[74:75], v[68:69]
	v_lshlrev_b32_e32 v66, 16, v229
	v_and_b32_e32 v67, 0xffff0000, v229
	v_pk_add_f32 v[66:67], v[76:77], v[66:67]
	v_cvt_pk_bf16_f32 v68, v68, v69
	v_cvt_pk_bf16_f32 v69, v66, v67
	v_and_b32_e32 v67, 0xffff0000, v68
	v_lshlrev_b32_e32 v66, 16, v68
	v_mul_f32_e32 v67, v67, v67
	global_store_dwordx2 v[100:101], v[68:69], off offset:96
	v_lshlrev_b32_e32 v68, 16, v69
	v_fmac_f32_e32 v67, v66, v66
	v_and_b32_e32 v69, 0xffff0000, v69
	v_fmac_f32_e32 v67, v68, v68
	v_fmac_f32_e32 v67, v69, v69
	v_add_f32_e32 v68, v70, v67
	s_waitcnt vmcnt(7)
	v_lshlrev_b32_e32 v70, 16, v230
	v_and_b32_e32 v71, 0xffff0000, v230
	v_pk_add_f32 v[70:71], v[78:79], v[70:71]
	v_lshlrev_b32_e32 v66, 16, v231
	v_and_b32_e32 v67, 0xffff0000, v231
	v_pk_add_f32 v[66:67], v[80:81], v[66:67]
	v_cvt_pk_bf16_f32 v70, v70, v71
	v_cvt_pk_bf16_f32 v71, v66, v67
	v_and_b32_e32 v67, 0xffff0000, v70
	v_lshlrev_b32_e32 v66, 16, v70
	v_mul_f32_e32 v67, v67, v67
	v_lshlrev_b32_e32 v69, 16, v71
	v_fmac_f32_e32 v67, v66, v66
	global_store_dwordx2 v[100:101], v[70:71], off offset:112
	v_and_b32_e32 v70, 0xffff0000, v71
	v_fmac_f32_e32 v67, v69, v69
	v_fmac_f32_e32 v67, v70, v70
	v_add_f32_e32 v66, v68, v67
	ds_bpermute_b32 v67, v0, v66
	s_and_saveexec_b64 s[2:3], vcc
	s_cbranch_execz .LBB0_53
	s_waitcnt lgkmcnt(0)
	v_add_f32_e32 v66, v66, v67
	global_store_dword v[98:99], v66, off offset:128
; DI unsigned pack2(float a, float b) { fl2_t f; f.x = a; f.y = b; bf16x2_t r = __builtin_convertvector(f, bf16x2_t); return __builtin_bit_cast(unsigned, r); }
; DI float bflo(unsigned u) { return __uint_as_float(u << 16); }
; DI float bfhi(unsigned u) { return __uint_as_float(u & 0xffff0000u); }
;     ...
;     } else if (EPI == EPI_RES) {
;       float ss = 0.f;
; #pragma unroll
;       for (int j = 0; j < 2; ++j)
; #pragma unroll
;         for (int gq = 0; gq < 4; ++gq) {
;           u16* hp = p.hb + (size_t)m * 1024 + nw + j * 32 + 8 * gq + 4 * hh;
;           uint2 old = *(const uint2*)hp;
;           float h0 = bflo(old.x) + g.scale * acc[i][j][4 * gq + 0];
;           float h1 = bfhi(old.x) + g.scale * acc[i][j][4 * gq + 1];
;           float h2 = bflo(old.y) + g.scale * acc[i][j][4 * gq + 2];
;           float h3 = bfhi(old.y) + g.scale * acc[i][j][4 * gq + 3];
;           unsigned p0 = pack2(h0, h1), p1 = pack2(h2, h3);
;           *(uint2*)hp = make_uint2(p0, p1);
;           float r0 = bflo(p0), r1 = bfhi(p0), r2 = bflo(p1), r3 = bfhi(p1);
;           ss += r0 * r0 + r1 * r1 + r2 * r2 + r3 * r3;
;         }
;       ss += __shfl_xor(ss, 32);
;       if (hh == 0) p.ssq[(size_t)(nw >> 6) * TP + m] = ss;
.LBB0_53:
	s_or_b64 exec, exec, s[2:3]
	v_or_b32_e32 v66, 64, v130
	s_waitcnt lgkmcnt(0)
	v_ashrrev_i32_e32 v67, 31, v66
	v_lshlrev_b64 v[66:67], 11, v[66:67]
	v_lshl_add_u64 v[66:67], v[132:133], 0, v[66:67]
	global_load_dwordx2 v[216:217], v[66:67], off
	global_load_dwordx2 v[218:219], v[66:67], off offset:16
	global_load_dwordx2 v[220:221], v[66:67], off offset:32
	global_load_dwordx2 v[222:223], v[66:67], off offset:48
	global_load_dwordx2 v[224:225], v[66:67], off offset:64
	global_load_dwordx2 v[226:227], v[66:67], off offset:80
	global_load_dwordx2 v[228:229], v[66:67], off offset:96
	global_load_dwordx2 v[230:231], v[66:67], off offset:112
	s_waitcnt vmcnt(7)
	v_lshlrev_b32_e32 v70, 16, v216
	v_and_b32_e32 v71, 0xffff0000, v216
	v_lshlrev_b32_e32 v68, 16, v217
	v_and_b32_e32 v69, 0xffff0000, v217
	v_pk_add_f32 v[50:51], v[50:51], v[70:71]
	v_pk_add_f32 v[52:53], v[52:53], v[68:69]
	v_cvt_pk_bf16_f32 v50, v50, v51
	v_cvt_pk_bf16_f32 v51, v52, v53
	global_store_dwordx2 v[66:67], v[50:51], off
	v_lshlrev_b32_e32 v52, 16, v50
	v_and_b32_e32 v50, 0xffff0000, v50
	v_mul_f32_e32 v68, v50, v50
	v_lshlrev_b32_e32 v53, 16, v51
	v_fmac_f32_e32 v68, v52, v52
	v_and_b32_e32 v51, 0xffff0000, v51
	v_fmac_f32_e32 v68, v53, v53
	v_fmac_f32_e32 v68, v51, v51
	s_waitcnt vmcnt(7)
	v_lshlrev_b32_e32 v52, 16, v218
	v_and_b32_e32 v53, 0xffff0000, v218
	v_pk_add_f32 v[52:53], v[54:55], v[52:53]
	v_lshlrev_b32_e32 v50, 16, v219
	v_and_b32_e32 v51, 0xffff0000, v219
	v_pk_add_f32 v[50:51], v[56:57], v[50:51]
	v_cvt_pk_bf16_f32 v52, v52, v53
	v_cvt_pk_bf16_f32 v53, v50, v51
	v_and_b32_e32 v51, 0xffff0000, v52
	v_lshlrev_b32_e32 v50, 16, v52
	v_mul_f32_e32 v51, v51, v51
	global_store_dwordx2 v[66:67], v[52:53], off offset:16
	v_lshlrev_b32_e32 v52, 16, v53
	v_fmac_f32_e32 v51, v50, v50
	v_and_b32_e32 v53, 0xffff0000, v53
	v_fmac_f32_e32 v51, v52, v52
	v_fmac_f32_e32 v51, v53, v53
	v_add_f32_e32 v54, v68, v51
	s_waitcnt vmcnt(7)
	v_lshlrev_b32_e32 v52, 16, v220
	v_and_b32_e32 v53, 0xffff0000, v220
	v_pk_add_f32 v[52:53], v[58:59], v[52:53]
	v_lshlrev_b32_e32 v50, 16, v221
	v_and_b32_e32 v51, 0xffff0000, v221
	v_pk_add_f32 v[50:51], v[60:61], v[50:51]
	v_cvt_pk_bf16_f32 v52, v52, v53
	v_cvt_pk_bf16_f32 v53, v50, v51
	v_and_b32_e32 v51, 0xffff0000, v52
	v_lshlrev_b32_e32 v50, 16, v52
	v_mul_f32_e32 v51, v51, v51
	global_store_dwordx2 v[66:67], v[52:53], off offset:32
	v_lshlrev_b32_e32 v52, 16, v53
	v_fmac_f32_e32 v51, v50, v50
	v_and_b32_e32 v53, 0xffff0000, v53
	v_fmac_f32_e32 v51, v52, v52
	v_fmac_f32_e32 v51, v53, v53
	v_add_f32_e32 v54, v54, v51
	s_waitcnt vmcnt(7)
	v_lshlrev_b32_e32 v52, 16, v222
	v_and_b32_e32 v53, 0xffff0000, v222
	v_pk_add_f32 v[52:53], v[62:63], v[52:53]
	v_lshlrev_b32_e32 v50, 16, v223
	v_and_b32_e32 v51, 0xffff0000, v223
	v_pk_add_f32 v[50:51], v[64:65], v[50:51]
	v_cvt_pk_bf16_f32 v52, v52, v53
	v_cvt_pk_bf16_f32 v53, v50, v51
	v_and_b32_e32 v51, 0xffff0000, v52
	v_lshlrev_b32_e32 v50, 16, v52
	v_mul_f32_e32 v51, v51, v51
	global_store_dwordx2 v[66:67], v[52:53], off offset:48
	v_lshlrev_b32_e32 v52, 16, v53
	v_fmac_f32_e32 v51, v50, v50
	v_and_b32_e32 v53, 0xffff0000, v53
	v_fmac_f32_e32 v51, v52, v52
	v_fmac_f32_e32 v51, v53, v53
	v_add_f32_e32 v54, v54, v51
	s_waitcnt vmcnt(7)
	v_lshlrev_b32_e32 v52, 16, v224
	v_and_b32_e32 v53, 0xffff0000, v224
	v_lshlrev_b32_e32 v50, 16, v225
	v_and_b32_e32 v51, 0xffff0000, v225
	v_pk_add_f32 v[34:35], v[34:35], v[52:53]
	v_pk_add_f32 v[36:37], v[36:37], v[50:51]
	v_cvt_pk_bf16_f32 v34, v34, v35
	v_cvt_pk_bf16_f32 v35, v36, v37
	global_store_dwordx2 v[66:67], v[34:35], off offset:64
	v_lshlrev_b32_e32 v36, 16, v34
	v_and_b32_e32 v34, 0xffff0000, v34
	v_mul_f32_e32 v34, v34, v34
	v_lshlrev_b32_e32 v37, 16, v35
	v_fmac_f32_e32 v34, v36, v36
	v_and_b32_e32 v35, 0xffff0000, v35
	v_fmac_f32_e32 v34, v37, v37
	v_fmac_f32_e32 v34, v35, v35
	v_add_f32_e32 v50, v54, v34
	s_waitcnt vmcnt(7)
	v_lshlrev_b32_e32 v36, 16, v226
	v_and_b32_e32 v37, 0xffff0000, v226
	v_pk_add_f32 v[36:37], v[38:39], v[36:37]
	v_lshlrev_b32_e32 v34, 16, v227
	v_and_b32_e32 v35, 0xffff0000, v227
	v_pk_add_f32 v[34:35], v[40:41], v[34:35]
	v_cvt_pk_bf16_f32 v36, v36, v37
	v_cvt_pk_bf16_f32 v37, v34, v35
	v_and_b32_e32 v35, 0xffff0000, v36
	v_lshlrev_b32_e32 v34, 16, v36
	v_mul_f32_e32 v35, v35, v35
	global_store_dwordx2 v[66:67], v[36:37], off offset:80
	v_lshlrev_b32_e32 v36, 16, v37
	v_fmac_f32_e32 v35, v34, v34
	v_and_b32_e32 v37, 0xffff0000, v37
	v_fmac_f32_e32 v35, v36, v36
	v_fmac_f32_e32 v35, v37, v37
	v_add_f32_e32 v38, v50, v35
	s_waitcnt vmcnt(7)
	v_lshlrev_b32_e32 v36, 16, v228
	v_and_b32_e32 v37, 0xffff0000, v228
	v_pk_add_f32 v[36:37], v[42:43], v[36:37]
	v_lshlrev_b32_e32 v34, 16, v229
	v_and_b32_e32 v35, 0xffff0000, v229
	v_pk_add_f32 v[34:35], v[44:45], v[34:35]
	v_cvt_pk_bf16_f32 v36, v36, v37
	v_cvt_pk_bf16_f32 v37, v34, v35
	v_and_b32_e32 v35, 0xffff0000, v36
	v_lshlrev_b32_e32 v34, 16, v36
	v_mul_f32_e32 v35, v35, v35
	global_store_dwordx2 v[66:67], v[36:37], off offset:96
	v_lshlrev_b32_e32 v36, 16, v37
	v_fmac_f32_e32 v35, v34, v34
	v_and_b32_e32 v37, 0xffff0000, v37
	v_fmac_f32_e32 v35, v36, v36
	v_fmac_f32_e32 v35, v37, v37
	v_add_f32_e32 v36, v38, v35
	s_waitcnt vmcnt(7)
	v_lshlrev_b32_e32 v38, 16, v230
	v_and_b32_e32 v39, 0xffff0000, v230
	v_pk_add_f32 v[38:39], v[46:47], v[38:39]
	v_lshlrev_b32_e32 v34, 16, v231
	v_and_b32_e32 v35, 0xffff0000, v231
	v_pk_add_f32 v[34:35], v[48:49], v[34:35]
	v_cvt_pk_bf16_f32 v38, v38, v39
	v_cvt_pk_bf16_f32 v39, v34, v35
	v_and_b32_e32 v35, 0xffff0000, v38
	v_lshlrev_b32_e32 v34, 16, v38
	v_mul_f32_e32 v35, v35, v35
	v_lshlrev_b32_e32 v37, 16, v39
	v_fmac_f32_e32 v35, v34, v34
	global_store_dwordx2 v[66:67], v[38:39], off offset:112
	v_and_b32_e32 v38, 0xffff0000, v39
	v_fmac_f32_e32 v35, v37, v37
	v_fmac_f32_e32 v35, v38, v38
	v_add_f32_e32 v34, v36, v35
	ds_bpermute_b32 v35, v0, v34
	s_and_saveexec_b64 s[2:3], vcc
	s_cbranch_execz .LBB0_55
	s_waitcnt lgkmcnt(0)
	v_add_f32_e32 v34, v34, v35
	global_store_dword v[98:99], v34, off offset:256
; DI unsigned pack2(float a, float b) { fl2_t f; f.x = a; f.y = b; bf16x2_t r = __builtin_convertvector(f, bf16x2_t); return __builtin_bit_cast(unsigned, r); }
; DI float bflo(unsigned u) { return __uint_as_float(u << 16); }
; DI float bfhi(unsigned u) { return __uint_as_float(u & 0xffff0000u); }
;     ...
;     } else if (EPI == EPI_RES) {
;       float ss = 0.f;
; #pragma unroll
;       for (int j = 0; j < 2; ++j)
; #pragma unroll
;         for (int gq = 0; gq < 4; ++gq) {
;           u16* hp = p.hb + (size_t)m * 1024 + nw + j * 32 + 8 * gq + 4 * hh;
;           uint2 old = *(const uint2*)hp;
;           float h0 = bflo(old.x) + g.scale * acc[i][j][4 * gq + 0];
;           float h1 = bfhi(old.x) + g.scale * acc[i][j][4 * gq + 1];
;           float h2 = bflo(old.y) + g.scale * acc[i][j][4 * gq + 2];
;           float h3 = bfhi(old.y) + g.scale * acc[i][j][4 * gq + 3];
;           unsigned p0 = pack2(h0, h1), p1 = pack2(h2, h3);
;           *(uint2*)hp = make_uint2(p0, p1);
;           float r0 = bflo(p0), r1 = bfhi(p0), r2 = bflo(p1), r3 = bfhi(p1);
;           ss += r0 * r0 + r1 * r1 + r2 * r2 + r3 * r3;
;         }
;       ss += __shfl_xor(ss, 32);
;       if (hh == 0) p.ssq[(size_t)(nw >> 6) * TP + m] = ss;
.LBB0_55:
	s_or_b64 exec, exec, s[2:3]
	v_or_b32_e32 v34, 0x60, v130
	s_waitcnt lgkmcnt(0)
	v_ashrrev_i32_e32 v35, 31, v34
	v_lshlrev_b64 v[34:35], 11, v[34:35]
	v_lshl_add_u64 v[34:35], v[132:133], 0, v[34:35]
	global_load_dwordx2 v[216:217], v[34:35], off
	global_load_dwordx2 v[218:219], v[34:35], off offset:16
	global_load_dwordx2 v[220:221], v[34:35], off offset:32
	global_load_dwordx2 v[222:223], v[34:35], off offset:48
	global_load_dwordx2 v[224:225], v[34:35], off offset:64
	global_load_dwordx2 v[226:227], v[34:35], off offset:80
	global_load_dwordx2 v[228:229], v[34:35], off offset:96
	global_load_dwordx2 v[230:231], v[34:35], off offset:112
	s_waitcnt vmcnt(7)
	v_lshlrev_b32_e32 v38, 16, v216
	v_and_b32_e32 v39, 0xffff0000, v216
	v_lshlrev_b32_e32 v36, 16, v217
	v_and_b32_e32 v37, 0xffff0000, v217
	v_pk_add_f32 v[18:19], v[18:19], v[38:39]
	v_pk_add_f32 v[20:21], v[20:21], v[36:37]
	v_cvt_pk_bf16_f32 v18, v18, v19
	v_cvt_pk_bf16_f32 v19, v20, v21
	global_store_dwordx2 v[34:35], v[18:19], off
	v_lshlrev_b32_e32 v20, 16, v18
	v_and_b32_e32 v18, 0xffff0000, v18
	v_mul_f32_e32 v36, v18, v18
	v_lshlrev_b32_e32 v21, 16, v19
	v_fmac_f32_e32 v36, v20, v20
	v_and_b32_e32 v19, 0xffff0000, v19
	v_fmac_f32_e32 v36, v21, v21
	v_fmac_f32_e32 v36, v19, v19
	s_waitcnt vmcnt(7)
	v_lshlrev_b32_e32 v20, 16, v218
	v_and_b32_e32 v21, 0xffff0000, v218
	v_pk_add_f32 v[20:21], v[22:23], v[20:21]
	v_lshlrev_b32_e32 v18, 16, v219
	v_and_b32_e32 v19, 0xffff0000, v219
	v_pk_add_f32 v[18:19], v[24:25], v[18:19]
	v_cvt_pk_bf16_f32 v20, v20, v21
	v_cvt_pk_bf16_f32 v21, v18, v19
	v_and_b32_e32 v19, 0xffff0000, v20
	v_lshlrev_b32_e32 v18, 16, v20
	v_mul_f32_e32 v19, v19, v19
	global_store_dwordx2 v[34:35], v[20:21], off offset:16
	v_lshlrev_b32_e32 v20, 16, v21
	v_fmac_f32_e32 v19, v18, v18
	v_and_b32_e32 v21, 0xffff0000, v21
	v_fmac_f32_e32 v19, v20, v20
	v_fmac_f32_e32 v19, v21, v21
	v_add_f32_e32 v22, v36, v19
	s_waitcnt vmcnt(7)
	v_lshlrev_b32_e32 v20, 16, v220
	v_and_b32_e32 v21, 0xffff0000, v220
	v_pk_add_f32 v[20:21], v[26:27], v[20:21]
	v_lshlrev_b32_e32 v18, 16, v221
	v_and_b32_e32 v19, 0xffff0000, v221
	v_pk_add_f32 v[18:19], v[28:29], v[18:19]
	v_cvt_pk_bf16_f32 v20, v20, v21
	v_cvt_pk_bf16_f32 v21, v18, v19
	v_and_b32_e32 v19, 0xffff0000, v20
	v_lshlrev_b32_e32 v18, 16, v20
	v_mul_f32_e32 v19, v19, v19
	global_store_dwordx2 v[34:35], v[20:21], off offset:32
	v_lshlrev_b32_e32 v20, 16, v21
	v_fmac_f32_e32 v19, v18, v18
	v_and_b32_e32 v21, 0xffff0000, v21
	v_fmac_f32_e32 v19, v20, v20
	v_fmac_f32_e32 v19, v21, v21
	v_add_f32_e32 v22, v22, v19
	s_waitcnt vmcnt(7)
	v_lshlrev_b32_e32 v20, 16, v222
	v_and_b32_e32 v21, 0xffff0000, v222
	v_pk_add_f32 v[20:21], v[30:31], v[20:21]
	v_lshlrev_b32_e32 v18, 16, v223
	v_and_b32_e32 v19, 0xffff0000, v223
	v_pk_add_f32 v[18:19], v[32:33], v[18:19]
	v_cvt_pk_bf16_f32 v20, v20, v21
	v_cvt_pk_bf16_f32 v21, v18, v19
	v_and_b32_e32 v19, 0xffff0000, v20
	v_lshlrev_b32_e32 v18, 16, v20
	v_mul_f32_e32 v19, v19, v19
	global_store_dwordx2 v[34:35], v[20:21], off offset:48
	v_lshlrev_b32_e32 v20, 16, v21
	v_fmac_f32_e32 v19, v18, v18
	v_and_b32_e32 v21, 0xffff0000, v21
	v_fmac_f32_e32 v19, v20, v20
	v_fmac_f32_e32 v19, v21, v21
	v_add_f32_e32 v22, v22, v19
	s_waitcnt vmcnt(7)
	v_lshlrev_b32_e32 v20, 16, v224
	v_and_b32_e32 v21, 0xffff0000, v224
	v_lshlrev_b32_e32 v18, 16, v225
	v_and_b32_e32 v19, 0xffff0000, v225
	v_pk_add_f32 v[2:3], v[2:3], v[20:21]
	v_pk_add_f32 v[4:5], v[4:5], v[18:19]
	v_cvt_pk_bf16_f32 v2, v2, v3
	v_cvt_pk_bf16_f32 v3, v4, v5
	global_store_dwordx2 v[34:35], v[2:3], off offset:64
	v_lshlrev_b32_e32 v4, 16, v2
	v_and_b32_e32 v2, 0xffff0000, v2
	v_mul_f32_e32 v2, v2, v2
	v_lshlrev_b32_e32 v5, 16, v3
	v_fmac_f32_e32 v2, v4, v4
	v_and_b32_e32 v3, 0xffff0000, v3
	v_fmac_f32_e32 v2, v5, v5
	v_fmac_f32_e32 v2, v3, v3
	v_add_f32_e32 v18, v22, v2
	s_waitcnt vmcnt(7)
	v_lshlrev_b32_e32 v4, 16, v226
	v_and_b32_e32 v5, 0xffff0000, v226
	v_pk_add_f32 v[4:5], v[6:7], v[4:5]
	v_lshlrev_b32_e32 v2, 16, v227
	v_and_b32_e32 v3, 0xffff0000, v227
	v_pk_add_f32 v[2:3], v[8:9], v[2:3]
	v_cvt_pk_bf16_f32 v4, v4, v5
	v_cvt_pk_bf16_f32 v5, v2, v3
	v_and_b32_e32 v3, 0xffff0000, v4
	v_lshlrev_b32_e32 v2, 16, v4
	v_mul_f32_e32 v3, v3, v3
	global_store_dwordx2 v[34:35], v[4:5], off offset:80
	v_lshlrev_b32_e32 v4, 16, v5
	v_fmac_f32_e32 v3, v2, v2
	v_and_b32_e32 v5, 0xffff0000, v5
	v_fmac_f32_e32 v3, v4, v4
	v_fmac_f32_e32 v3, v5, v5
	v_add_f32_e32 v6, v18, v3
	s_waitcnt vmcnt(7)
	v_lshlrev_b32_e32 v4, 16, v228
	v_and_b32_e32 v5, 0xffff0000, v228
	v_pk_add_f32 v[4:5], v[10:11], v[4:5]
	v_lshlrev_b32_e32 v2, 16, v229
	v_and_b32_e32 v3, 0xffff0000, v229
	v_pk_add_f32 v[2:3], v[12:13], v[2:3]
	v_cvt_pk_bf16_f32 v4, v4, v5
	v_cvt_pk_bf16_f32 v5, v2, v3
	v_and_b32_e32 v3, 0xffff0000, v4
	v_lshlrev_b32_e32 v2, 16, v4
	v_mul_f32_e32 v3, v3, v3
	global_store_dwordx2 v[34:35], v[4:5], off offset:96
	v_lshlrev_b32_e32 v4, 16, v5
	v_fmac_f32_e32 v3, v2, v2
	v_and_b32_e32 v5, 0xffff0000, v5
	v_fmac_f32_e32 v3, v4, v4
	v_fmac_f32_e32 v3, v5, v5
	v_add_f32_e32 v4, v6, v3
	s_waitcnt vmcnt(7)
	v_lshlrev_b32_e32 v6, 16, v230
	v_and_b32_e32 v7, 0xffff0000, v230
	v_pk_add_f32 v[6:7], v[14:15], v[6:7]
	v_lshlrev_b32_e32 v2, 16, v231
	v_and_b32_e32 v3, 0xffff0000, v231
	v_pk_add_f32 v[2:3], v[16:17], v[2:3]
	v_cvt_pk_bf16_f32 v6, v6, v7
	v_cvt_pk_bf16_f32 v7, v2, v3
	v_and_b32_e32 v3, 0xffff0000, v6
	v_lshlrev_b32_e32 v2, 16, v6
	v_mul_f32_e32 v3, v3, v3
	v_lshlrev_b32_e32 v5, 16, v7
	v_fmac_f32_e32 v3, v2, v2
	global_store_dwordx2 v[34:35], v[6:7], off offset:112
	v_and_b32_e32 v6, 0xffff0000, v7
	v_fmac_f32_e32 v3, v5, v5
	v_fmac_f32_e32 v3, v6, v6
	v_add_f32_e32 v2, v4, v3
	ds_bpermute_b32 v0, v0, v2
	s_and_saveexec_b64 s[2:3], vcc
	s_cbranch_execz .LBB0_35
	s_waitcnt lgkmcnt(0)
	v_add_f32_e32 v0, v2, v0
	global_store_dword v[98:99], v0, off offset:384
	s_branch .LBB0_35

;     ...
;     auto issue_at = [&](int mm0, int nn0, int kt, int buf) {
;       char* lb = L0 + buf * BUFB;
; #pragma unroll
;       for (int i = 0; i < 4; ++i) {
;         const int seg = wv * 4 + i, row = seg * 8 + gl_row;
;         const int c = (lane & 7) ^ ((row >> 1) & 7);
;         const u16* ap = (kt < g.split) ? g.a0 + (size_t)(mm0 + row) * g.ld0 + kt * g.ks0 : g.a1 + (size_t)(mm0 + row) * g.ld1 + (kt - g.split) * 64;
;         __builtin_amdgcn_global_load_lds((const unsigned*)(ap + c * 8), (__attribute__((address_space(3))) unsigned*)(lb + seg * 1024 + lane * 16), 16, 0, 0);
;       }
; #pragma unroll
;       for (int i = 0; i < BN / 64; ++i) {
;         const int seg = wv * (BN / 64) + i, row = seg * 8 + gl_row;
;         const int c = (lane & 7) ^ ((row >> 1) & 7);
;         __builtin_amdgcn_global_load_lds((const unsigned*)(g.W + (size_t)(nn0 + row) * g.K + kt * 64 + c * 8),
;                                          (__attribute__((address_space(3))) unsigned*)(lb + 256 * 128 + seg * 1024 + lane * 16), 16, 0, 0);
;       }
;     };
;     auto issue = [&](int kt, int buf) { issue_at(m0, n0, kt, buf); };
;     auto compute2 = [&](int buf) {
;       const char* lb = L0 + buf * BUFB;
; #pragma unroll
;       for (int ks = 0; ks < 4; ++ks) {
;         const int c = ks * 2 + hh;
;         bf16x8 wf[2], xf[MI];
; #pragma unroll
;         for (int j = 0; j < 2; ++j) { const int r = wn * 64 + j * 32 + l32; wf[j] = *(const bf16x8*)(lb + 256 * 128 + r * 128 + ((c ^ ((r >> 1) & 7)) << 4)); }
; #pragma unroll
;         for (int i = 0; i < MI; ++i) { const int r = wm * (MI * 32) + i * 32 + l32; xf[i] = *(const bf16x8*)(lb + r * 128 + ((c ^ ((r >> 1) & 7)) << 4)); }
; #pragma unroll
;         for (int i = 0; i < MI; ++i) {
;           acc[i][0] = MFMA(wf[0], xf[i], acc[i][0]);
;           acc[i][1] = MFMA(wf[1], xf[i], acc[i][1]);
;         }
;       }
;     };
;     if (NBUF == 3) {
;       issue(0, 0);
;       if (nk > 1) { issue(1, 1); if (BN == 128) asm volatile("s_waitcnt vmcnt(6)" ::: "memory"); else asm volatile("s_waitcnt vmcnt(5)" ::: "memory"); }
;       else asm volatile("s_waitcnt vmcnt(0)" ::: "memory");
;       asm volatile("s_waitcnt lgkmcnt(0)" ::: "memory");
;       __builtin_amdgcn_s_barrier();
;       int buf = 0;
;       for (int kt = 0; kt < nk; ++kt) {
;         const int b2 = buf == 0 ? 2 : buf - 1;
;         if (kt + 2 < nk) issue(kt + 2, b2);
.LBB0_60:
	s_waitcnt vmcnt(4)
	v_mov_b32_e32 v14, v179
	s_waitcnt vmcnt(3)
	v_mov_b64_e32 v[4:5], s[46:47]
	v_ashrrev_i32_e32 v15, 6, v14
	s_waitcnt lgkmcnt(0)
	v_bfe_u32 v0, v14, 4, 2
	v_bfe_u32 v12, v14, 3, 3
	v_xor_b32_e32 v0, v0, v14
	v_lshl_add_u32 v61, v15, 5, v184
	v_or_b32_e32 v2, v61, v12
	s_movk_i32 s3, 0x600
	v_lshlrev_b32_e32 v0, 4, v0
	v_lshlrev_b32_e32 v13, 2, v15
	v_mad_i64_i32 v[6:7], s[8:9], v2, s3, v[4:5]
	v_and_b32_e32 v0, 0x70, v0
	s_waitcnt vmcnt(2)
	v_or_b32_e32 v10, 1, v13
	v_lshl_add_u64 v[50:51], v[6:7], 0, v[0:1]
	v_lshl_or_b32 v6, v10, 3, v12
	v_lshrrev_b32_e32 v7, 1, v6
	v_xor_b32_e32 v11, v7, v14
	v_add_u32_e32 v6, 0x8000, v6
	v_lshlrev_b32_e32 v11, 4, v11
	v_mad_i64_i32 v[8:9], s[8:9], v6, s3, v[4:5]
	v_and_b32_e32 v36, 0x70, v11
	v_mov_b32_e32 v37, v1
	s_waitcnt vmcnt(1)
	v_or_b32_e32 v19, 2, v13
	v_lshl_add_u64 v[52:53], v[8:9], 0, v[36:37]
	v_lshl_or_b32 v8, v19, 3, v12
	v_lshrrev_b32_e32 v9, 1, v8
	s_waitcnt vmcnt(0)
	v_xor_b32_e32 v20, v9, v14
	v_add_u32_e32 v8, 0x8000, v8
	v_lshlrev_b32_e32 v20, 4, v20
	v_or_b32_e32 v13, 3, v13
	v_lshlrev_b32_e32 v18, 10, v10
	v_mad_i64_i32 v[10:11], s[8:9], v8, s3, v[4:5]
	v_and_b32_e32 v38, 0x70, v20
	v_mov_b32_e32 v39, v1
	v_lshl_or_b32 v20, v13, 3, v12
	v_lshl_add_u64 v[54:55], v[10:11], 0, v[38:39]
	v_add_u32_e32 v10, 0x8000, v20
	v_lshrrev_b32_e32 v20, 1, v20
	v_xor_b32_e32 v20, v20, v14
	v_lshlrev_b32_e32 v20, 4, v20
	v_mad_i64_i32 v[4:5], s[8:9], v10, s3, v[4:5]
	v_and_b32_e32 v40, 0x70, v20
	v_mov_b32_e32 v41, v1
	v_lshl_add_u64 v[56:57], v[4:5], 0, v[40:41]
	v_lshl_or_b32 v4, v15, 3, v12
	v_and_b32_e32 v58, 63, v14
	v_lshrrev_b32_e32 v5, 1, v4
	v_add_u32_e32 v4, s2, v4
	v_lshlrev_b32_e32 v16, 12, v15
	v_lshlrev_b32_e32 v17, 4, v58
	v_xor_b32_e32 v12, v5, v14
	v_ashrrev_i32_e32 v5, 31, v4
	v_add3_u32 v73, 0, v16, v17
	v_lshlrev_b64 v[4:5], 11, v[4:5]
	v_lshlrev_b32_e32 v12, 4, v12
	v_readfirstlane_b32 s53, v73
	v_add3_u32 v78, 0, v18, v17
	v_lshlrev_b32_e32 v19, 10, v19
	v_lshlrev_b32_e32 v20, 10, v13
	v_lshl_add_u64 v[4:5], s[48:49], 0, v[4:5]
	v_and_b32_e32 v12, 0x70, v12
	v_mov_b32_e32 v13, v1
	s_mov_b32 m0, s53
	v_readfirstlane_b32 s54, v78
	v_add3_u32 v80, 0, v19, v17
	v_lshl_add_u64 v[34:35], v[4:5], 0, v[12:13]
	v_lshlrev_b32_e32 v12, 10, v15
	global_load_lds_dwordx4 v[50:51], off
	s_mov_b32 m0, s54
	v_readfirstlane_b32 s55, v80
	v_add3_u32 v65, 0, v20, v17
	v_add_u32_e32 v4, 0, v12
	global_load_lds_dwordx4 v[52:53], off
	s_mov_b32 m0, s55
	v_readfirstlane_b32 s50, v65
	v_add3_u32 v67, v4, v17, s89
	global_load_lds_dwordx4 v[54:55], off
	s_mov_b32 m0, s50
	v_readfirstlane_b32 s51, v67
	v_add_u32_e32 v72, 0xa000, v73
	global_load_lds_dwordx4 v[56:57], off
	s_mov_b32 m0, s51
	s_mov_b64 s[8:9], 0xc0
	v_readfirstlane_b32 s52, v72
	v_add_u32_e32 v13, 0xa000, v78
	global_load_lds_dwordx4 v[34:35], off
	v_lshl_add_u64 v[4:5], v[50:51], 0, s[8:9]
	s_mov_b32 m0, s52
	v_readfirstlane_b32 s14, v13
	v_add_u32_e32 v13, 0xa000, v80
	global_load_lds_dwordx4 v[4:5], off
	v_lshl_add_u64 v[4:5], v[52:53], 0, s[8:9]
	s_mov_b32 m0, s14
	v_readfirstlane_b32 s41, v13
	global_load_lds_dwordx4 v[4:5], off
	v_lshl_add_u64 v[4:5], v[54:55], 0, s[8:9]
	s_mov_b32 m0, s41
	v_add_u32_e32 v13, 0xa000, v65
	global_load_lds_dwordx4 v[4:5], off
	v_lshl_add_u64 v[4:5], v[56:57], 0, s[8:9]
	v_readfirstlane_b32 s9, v13
	v_add3_u32 v13, s12, v12, v17
	s_mov_b32 m0, s9
	v_readfirstlane_b32 s40, v13
	global_load_lds_dwordx4 v[4:5], off
	v_lshl_add_u64 v[4:5], v[34:35], 0, s[26:27]
	s_mov_b32 m0, s40
	v_bfe_u32 v59, v14, 5, 1
	global_load_lds_dwordx4 v[4:5], off
	v_lshrrev_b32_e32 v4, 1, v14
	v_bfe_u32 v5, v14, 1, 3
	v_bitop3_b32 v4, v4, v59, 7 bitop3:0x6c
	v_ashrrev_i32_e32 v3, 31, v2
	v_lshlrev_b32_e32 v81, 4, v4
	v_bitop3_b32 v4, v59, v5, 2 bitop3:0x36
	v_ashrrev_i32_e32 v7, 31, v6
	v_lshlrev_b32_e32 v94, 4, v4
	v_bitop3_b32 v4, v59, v5, 4 bitop3:0x36
	v_lshlrev_b64 v[2:3], 11, v[2:3]
	v_ashrrev_i32_e32 v9, 31, v8
	v_lshlrev_b32_e32 v96, 4, v4
	v_bitop3_b32 v4, v59, v5, 6 bitop3:0x36
	v_lshl_add_u64 v[48:49], s[78:79], 0, v[2:3]
	v_lshlrev_b64 v[2:3], 11, v[6:7]
	v_add_u32_e32 v95, s13, v16
	v_ashrrev_i32_e32 v11, 31, v10
	v_lshlrev_b32_e32 v99, 4, v4
	v_lshl_add_u64 v[46:47], s[78:79], 0, v[2:3]
	v_lshlrev_b64 v[2:3], 11, v[8:9]
	v_add_u32_e32 v4, v95, v17
	v_lshl_add_u64 v[44:45], s[78:79], 0, v[2:3]
	v_lshlrev_b64 v[2:3], 11, v[10:11]
	v_readfirstlane_b32 s17, v4
	v_add3_u32 v4, s13, v18, v17
	s_waitcnt vmcnt(5)
	v_lshl_add_u64 v[42:43], s[78:79], 0, v[2:3]
	v_lshl_add_u64 v[2:3], v[50:51], 0, s[38:39]
	s_mov_b32 m0, s17
	v_readfirstlane_b32 s8, v4
	v_add3_u32 v4, s13, v19, v17
	v_and_b32_e32 v60, 31, v14
	s_waitcnt lgkmcnt(0)
	s_barrier
; #define MFMA(a, b, c) __builtin_amdgcn_mfma_f32_32x32x16_bf16((a), (b), (c), 0, 0, 0)
;     ...
;     auto compute2 = [&](int buf) {
;       const char* lb = L0 + buf * BUFB;
; #pragma unroll
;       for (int ks = 0; ks < 4; ++ks) {
;         const int c = ks * 2 + hh;
;         bf16x8 wf[2], xf[MI];
; #pragma unroll
;         for (int j = 0; j < 2; ++j) { const int r = wn * 64 + j * 32 + l32; wf[j] = *(const bf16x8*)(lb + 256 * 128 + r * 128 + ((c ^ ((r >> 1) & 7)) << 4)); }
; #pragma unroll
;         for (int i = 0; i < MI; ++i) { const int r = wm * (MI * 32) + i * 32 + l32; xf[i] = *(const bf16x8*)(lb + r * 128 + ((c ^ ((r >> 1) & 7)) << 4)); }
; #pragma unroll
;         for (int i = 0; i < MI; ++i) {
;           acc[i][0] = MFMA(wf[0], xf[i], acc[i][0]);
;           acc[i][1] = MFMA(wf[1], xf[i], acc[i][1]);
;         }
;       }
;     };
;     ...
;       __builtin_amdgcn_s_barrier();
;       int buf = 0;
;       for (int kt = 0; kt < nk; ++kt) {
;         const int b2 = buf == 0 ? 2 : buf - 1;
;         if (kt + 2 < nk) issue(kt + 2, b2);
;         compute2(buf);
;         if (kt + 2 < nk) { if (BN == 128) asm volatile("s_waitcnt vmcnt(6)" ::: "memory"); else asm volatile("s_waitcnt vmcnt(5)" ::: "memory"); }
;         else asm volatile("s_waitcnt vmcnt(0)" ::: "memory");
;         asm volatile("s_waitcnt lgkmcnt(0)" ::: "memory");
;         __builtin_amdgcn_s_barrier();
;         buf = buf == 2 ? 0 : buf + 1;
;       }
	global_load_lds_dwordx4 v[2:3], off
	v_lshl_add_u64 v[2:3], v[52:53], 0, s[38:39]
	s_mov_b32 m0, s8
	v_readfirstlane_b32 s16, v4
	v_add3_u32 v4, s13, v20, v17
	v_lshlrev_b32_e32 v98, 7, v60
	global_load_lds_dwordx4 v[2:3], off
	v_lshl_add_u64 v[2:3], v[54:55], 0, s[38:39]
	s_mov_b32 m0, s16
	v_readfirstlane_b32 s3, v4
	v_add3_u32 v4, s33, v12, v17
	global_load_lds_dwordx4 v[2:3], off
	v_lshl_add_u64 v[2:3], v[56:57], 0, s[38:39]
	s_mov_b32 m0, s3
	v_readfirstlane_b32 s15, v4
	v_add_u32_e32 v79, 0, v98
	global_load_lds_dwordx4 v[2:3], off
	v_lshl_add_u64 v[2:3], v[34:35], 0, s[90:91]
	s_mov_b32 m0, s15
	v_add_u32_e32 v90, v79, v16
	global_load_lds_dwordx4 v[2:3], off
	v_add_u32_e32 v62, v79, v81
	v_add_u32_e32 v63, v90, v81
	ds_read_b128 v[2:5], v62 offset:32768
	ds_read_b128 v[6:9], v62 offset:36864
	ds_read_b128 v[10:13], v63
	s_waitcnt lgkmcnt(0)
	v_mfma_f32_32x32x16_bf16 v[18:33], v[2:5], v[10:13], 0
	v_add_u32_e32 v64, v79, v94
	v_add_u32_e32 v66, v90, v94
	ds_read_b128 v[68:71], v64 offset:32768
	ds_read_b128 v[74:77], v64 offset:36864
	ds_read_b128 v[82:85], v66
	s_mov_b64 s[56:57], 0x240
	s_mov_b32 m0, s53
	v_add_u32_e32 v100, v95, v98
	v_mfma_f32_32x32x16_bf16 v[2:17], v[6:9], v[10:13], 0
	s_mov_b64 s[58:59], 0x540
	v_lshl_add_u64 v[48:49], v[48:49], 0, v[0:1]
	v_lshl_add_u64 v[46:47], v[46:47], 0, v[36:37]
	v_lshl_add_u64 v[38:39], v[44:45], 0, v[38:39]
	v_lshl_add_u64 v[36:37], v[42:43], 0, v[40:41]
	s_mov_b64 s[60:61], 0x400
	v_lshl_add_u64 v[40:41], v[34:35], 0, s[60:61]
	s_waitcnt lgkmcnt(0)
	v_mfma_f32_32x32x16_bf16 v[18:33], v[68:71], v[82:85], v[18:33]
	v_add_u32_e32 v68, v79, v96
	v_add_u32_e32 v69, v90, v96
	v_add_u32_e32 v70, v79, v99
	v_add_u32_e32 v71, v90, v99
	v_add3_u32 v79, s33, v81, v98
	v_lshlrev_b32_e32 v0, 3, v59
	v_mfma_f32_32x32x16_bf16 v[2:17], v[74:77], v[82:85], v[2:17]
	ds_read_b128 v[74:77], v68 offset:32768
	ds_read_b128 v[82:85], v68 offset:36864
	ds_read_b128 v[86:89], v69
	s_waitcnt lgkmcnt(0)
	v_mfma_f32_32x32x16_bf16 v[18:33], v[74:77], v[86:89], v[18:33]
	v_mfma_f32_32x32x16_bf16 v[2:17], v[82:85], v[86:89], v[2:17]
	ds_read_b128 v[74:77], v70 offset:32768
	ds_read_b128 v[82:85], v70 offset:36864
	ds_read_b128 v[86:89], v71
	s_waitcnt vmcnt(5)
	s_waitcnt lgkmcnt(0)
	s_barrier
	s_waitcnt lgkmcnt(0)
	v_mfma_f32_32x32x16_bf16 v[18:33], v[74:77], v[86:89], v[18:33]
	v_lshl_add_u64 v[74:75], v[50:51], 0, s[56:57]
	global_load_lds_dwordx4 v[74:75], off
	v_lshl_add_u64 v[74:75], v[52:53], 0, s[56:57]
	s_mov_b32 m0, s54
	v_add3_u32 v77, s12, v94, v98
	global_load_lds_dwordx4 v[74:75], off
	v_lshl_add_u64 v[74:75], v[54:55], 0, s[56:57]
	s_mov_b32 m0, s55
	v_mfma_f32_32x32x16_bf16 v[2:17], v[82:85], v[86:89], v[2:17]
	global_load_lds_dwordx4 v[74:75], off
	v_lshl_add_u64 v[74:75], v[56:57], 0, s[56:57]
	s_mov_b32 m0, s50
	v_add3_u32 v76, s12, v96, v98
	global_load_lds_dwordx4 v[74:75], off
	v_lshl_add_u64 v[74:75], v[34:35], 0, s[38:39]
	s_mov_b32 m0, s51
	s_mov_b64 s[56:57], 0x3c0
	global_load_lds_dwordx4 v[74:75], off
	v_add3_u32 v75, s12, v81, v98
	ds_read_b128 v[82:85], v75
	ds_read_b128 v[86:89], v75 offset:4096
	ds_read_b128 v[90:93], v63 offset:40960
	s_waitcnt lgkmcnt(0)
	v_mfma_f32_32x32x16_bf16 v[18:33], v[82:85], v[90:93], v[18:33]
	v_add3_u32 v74, s12, v99, v98
	s_mov_b32 m0, s52
	v_add_u32_e32 v81, v100, v81
	v_mfma_f32_32x32x16_bf16 v[2:17], v[86:89], v[90:93], v[2:17]
	ds_read_b128 v[82:85], v77
	ds_read_b128 v[86:89], v77 offset:4096
	ds_read_b128 v[90:93], v66 offset:40960
	s_waitcnt lgkmcnt(0)
	v_mfma_f32_32x32x16_bf16 v[18:33], v[82:85], v[90:93], v[18:33]
	v_mfma_f32_32x32x16_bf16 v[2:17], v[86:89], v[90:93], v[2:17]
	ds_read_b128 v[82:85], v76
	ds_read_b128 v[86:89], v76 offset:4096
	ds_read_b128 v[90:93], v69 offset:40960
	s_waitcnt lgkmcnt(0)
	v_mfma_f32_32x32x16_bf16 v[18:33], v[82:85], v[90:93], v[18:33]
	v_mfma_f32_32x32x16_bf16 v[2:17], v[86:89], v[90:93], v[2:17]
	ds_read_b128 v[82:85], v74
	ds_read_b128 v[86:89], v74 offset:4096
	ds_read_b128 v[90:93], v71 offset:40960
	s_waitcnt vmcnt(5)
	s_waitcnt lgkmcnt(0)
	s_barrier
	s_waitcnt lgkmcnt(0)
	v_mfma_f32_32x32x16_bf16 v[18:33], v[82:85], v[90:93], v[18:33]
	v_lshl_add_u64 v[82:83], v[50:51], 0, s[6:7]
	global_load_lds_dwordx4 v[82:83], off
	v_lshl_add_u64 v[82:83], v[52:53], 0, s[6:7]
	s_mov_b32 m0, s14
	s_nop 0
	global_load_lds_dwordx4 v[82:83], off
	v_lshl_add_u64 v[82:83], v[54:55], 0, s[6:7]
	s_mov_b32 m0, s41
	v_mfma_f32_32x32x16_bf16 v[2:17], v[86:89], v[90:93], v[2:17]
	global_load_lds_dwordx4 v[82:83], off
	v_lshl_add_u64 v[82:83], v[56:57], 0, s[6:7]
	s_mov_b32 m0, s9
	s_nop 0
	global_load_lds_dwordx4 v[82:83], off
	v_lshl_add_u64 v[82:83], v[34:35], 0, s[34:35]
	s_mov_b32 m0, s40
	s_nop 0
	global_load_lds_dwordx4 v[82:83], off
	ds_read_b128 v[82:85], v79
	ds_read_b128 v[86:89], v79 offset:4096
	ds_read_b128 v[90:93], v81
	s_waitcnt lgkmcnt(0)
	v_mfma_f32_32x32x16_bf16 v[18:33], v[82:85], v[90:93], v[18:33]
	v_add3_u32 v82, s33, v94, v98
	v_add_u32_e32 v83, v100, v94
	s_mov_b32 m0, s17
	v_mfma_f32_32x32x16_bf16 v[2:17], v[86:89], v[90:93], v[2:17]
	ds_read_b128 v[84:87], v82
	ds_read_b128 v[88:91], v82 offset:4096
	ds_read_b128 v[92:95], v83
	s_waitcnt lgkmcnt(0)
	v_mfma_f32_32x32x16_bf16 v[18:33], v[84:87], v[92:95], v[18:33]
	v_add3_u32 v84, s33, v96, v98
	v_add_u32_e32 v85, v100, v96
	v_mfma_f32_32x32x16_bf16 v[2:17], v[88:91], v[92:95], v[2:17]
	ds_read_b128 v[86:89], v84
	ds_read_b128 v[90:93], v84 offset:4096
	ds_read_b128 v[94:97], v85
	s_waitcnt lgkmcnt(0)
	v_mfma_f32_32x32x16_bf16 v[18:33], v[86:89], v[94:97], v[18:33]
	v_add3_u32 v86, s33, v99, v98
	v_add_u32_e32 v87, v100, v99
	v_mfma_f32_32x32x16_bf16 v[2:17], v[90:93], v[94:97], v[2:17]
	ds_read_b128 v[88:91], v86
	ds_read_b128 v[92:95], v86 offset:4096
	ds_read_b128 v[96:99], v87
	s_waitcnt vmcnt(5)
	s_waitcnt lgkmcnt(0)
	s_barrier
;     ...
;         const u16* ap = (kt < g.split) ? g.a0 + (size_t)(mm0 + row) * g.ld0 + kt * g.ks0 : g.a1 + (size_t)(mm0 + row) * g.ld1 + (kt - g.split) * 64;
;     ...
;       __builtin_amdgcn_s_barrier();
;       int buf = 0;
;       for (int kt = 0; kt < nk; ++kt) {
;         const int b2 = buf == 0 ? 2 : buf - 1;
;         if (kt + 2 < nk) issue(kt + 2, b2);
;         compute2(buf);
;         if (kt + 2 < nk) { if (BN == 128) asm volatile("s_waitcnt vmcnt(6)" ::: "memory"); else asm volatile("s_waitcnt vmcnt(5)" ::: "memory"); }
;         else asm volatile("s_waitcnt vmcnt(0)" ::: "memory");
;         asm volatile("s_waitcnt lgkmcnt(0)" ::: "memory");
;         __builtin_amdgcn_s_barrier();
;         buf = buf == 2 ? 0 : buf + 1;
;       }
	s_waitcnt lgkmcnt(0)
	v_mfma_f32_32x32x16_bf16 v[18:33], v[88:91], v[96:99], v[18:33]
	v_lshl_add_u64 v[88:89], v[50:51], 0, s[56:57]
	global_load_lds_dwordx4 v[88:89], off
	v_lshl_add_u64 v[88:89], v[52:53], 0, s[56:57]
	s_mov_b32 m0, s8
	s_nop 0
	global_load_lds_dwordx4 v[88:89], off
	v_lshl_add_u64 v[88:89], v[54:55], 0, s[56:57]
	s_mov_b32 m0, s16
	v_mfma_f32_32x32x16_bf16 v[2:17], v[92:95], v[96:99], v[2:17]
	global_load_lds_dwordx4 v[88:89], off
	v_lshl_add_u64 v[88:89], v[56:57], 0, s[56:57]
	s_mov_b32 m0, s3
	s_mov_b64 s[56:57], 0x480
	global_load_lds_dwordx4 v[88:89], off
	v_lshl_add_u64 v[88:89], v[34:35], 0, s[22:23]
	s_mov_b32 m0, s15
	s_nop 0
	global_load_lds_dwordx4 v[88:89], off
	ds_read_b128 v[88:91], v62 offset:32768
	ds_read_b128 v[92:95], v62 offset:36864
	ds_read_b128 v[96:99], v63
	s_waitcnt lgkmcnt(0)
	v_mfma_f32_32x32x16_bf16 v[18:33], v[88:91], v[96:99], v[18:33]
	s_mov_b32 m0, s53
	v_mfma_f32_32x32x16_bf16 v[2:17], v[92:95], v[96:99], v[2:17]
	ds_read_b128 v[88:91], v64 offset:32768
	ds_read_b128 v[92:95], v64 offset:36864
	ds_read_b128 v[96:99], v66
	s_waitcnt lgkmcnt(0)
	v_mfma_f32_32x32x16_bf16 v[18:33], v[88:91], v[96:99], v[18:33]
	v_mfma_f32_32x32x16_bf16 v[2:17], v[92:95], v[96:99], v[2:17]
	ds_read_b128 v[88:91], v68 offset:32768
	ds_read_b128 v[92:95], v68 offset:36864
	ds_read_b128 v[96:99], v69
	s_waitcnt lgkmcnt(0)
	v_mfma_f32_32x32x16_bf16 v[18:33], v[88:91], v[96:99], v[18:33]
	v_mfma_f32_32x32x16_bf16 v[2:17], v[92:95], v[96:99], v[2:17]
	ds_read_b128 v[88:91], v70 offset:32768
	ds_read_b128 v[92:95], v70 offset:36864
	ds_read_b128 v[96:99], v71
	s_waitcnt vmcnt(5)
	s_waitcnt lgkmcnt(0)
	s_barrier
	s_waitcnt lgkmcnt(0)
	v_mfma_f32_32x32x16_bf16 v[18:33], v[88:91], v[96:99], v[18:33]
	v_lshl_add_u64 v[88:89], v[50:51], 0, s[56:57]
	global_load_lds_dwordx4 v[88:89], off
	v_lshl_add_u64 v[88:89], v[52:53], 0, s[56:57]
	s_mov_b32 m0, s54
	v_lshl_add_u64 v[50:51], v[50:51], 0, s[58:59]
	global_load_lds_dwordx4 v[88:89], off
	v_lshl_add_u64 v[88:89], v[54:55], 0, s[56:57]
	s_mov_b32 m0, s55
	v_mfma_f32_32x32x16_bf16 v[2:17], v[92:95], v[96:99], v[2:17]
	global_load_lds_dwordx4 v[88:89], off
	v_lshl_add_u64 v[88:89], v[56:57], 0, s[56:57]
	s_mov_b32 m0, s50
	s_nop 0
	global_load_lds_dwordx4 v[88:89], off
	v_lshl_add_u64 v[88:89], v[34:35], 0, s[6:7]
	s_mov_b32 m0, s51
	s_nop 0
	global_load_lds_dwordx4 v[88:89], off
	ds_read_b128 v[88:91], v75
	ds_read_b128 v[92:95], v75 offset:4096
	ds_read_b128 v[96:99], v63 offset:40960
	s_waitcnt lgkmcnt(0)
	v_mfma_f32_32x32x16_bf16 v[18:33], v[88:91], v[96:99], v[18:33]
	s_mov_b32 m0, s52
	v_mfma_f32_32x32x16_bf16 v[2:17], v[92:95], v[96:99], v[2:17]
	ds_read_b128 v[88:91], v77
	ds_read_b128 v[92:95], v77 offset:4096
	ds_read_b128 v[96:99], v66 offset:40960
	s_waitcnt lgkmcnt(0)
	v_mfma_f32_32x32x16_bf16 v[18:33], v[88:91], v[96:99], v[18:33]
	v_mfma_f32_32x32x16_bf16 v[2:17], v[92:95], v[96:99], v[2:17]
	ds_read_b128 v[88:91], v76
	ds_read_b128 v[92:95], v76 offset:4096
	ds_read_b128 v[96:99], v69 offset:40960
	s_waitcnt lgkmcnt(0)
	v_mfma_f32_32x32x16_bf16 v[18:33], v[88:91], v[96:99], v[18:33]
	v_mfma_f32_32x32x16_bf16 v[2:17], v[92:95], v[96:99], v[2:17]
	ds_read_b128 v[88:91], v74
	ds_read_b128 v[92:95], v74 offset:4096
	ds_read_b128 v[96:99], v71 offset:40960
	s_waitcnt vmcnt(5)
	s_waitcnt lgkmcnt(0)
	s_barrier
	global_load_lds_dwordx4 v[50:51], off
	v_lshl_add_u64 v[50:51], v[52:53], 0, s[58:59]
	s_mov_b32 m0, s14
	s_waitcnt lgkmcnt(0)
	v_mfma_f32_32x32x16_bf16 v[18:33], v[88:91], v[96:99], v[18:33]
	global_load_lds_dwordx4 v[50:51], off
	v_lshl_add_u64 v[50:51], v[54:55], 0, s[58:59]
	s_mov_b32 m0, s41
	s_nop 0
	global_load_lds_dwordx4 v[50:51], off
	v_lshl_add_u64 v[50:51], v[56:57], 0, s[58:59]
	s_mov_b32 m0, s9
	s_mov_b64 s[58:59], 0x380
	global_load_lds_dwordx4 v[50:51], off
	v_lshl_add_u64 v[50:51], v[34:35], 0, s[58:59]
	s_mov_b32 m0, s40
	v_mfma_f32_32x32x16_bf16 v[2:17], v[92:95], v[96:99], v[2:17]
	global_load_lds_dwordx4 v[50:51], off
	ds_read_b128 v[50:53], v79
	ds_read_b128 v[54:57], v79 offset:4096
	ds_read_b128 v[88:91], v81
	s_mov_b32 m0, s17
	s_waitcnt lgkmcnt(0)
	v_mfma_f32_32x32x16_bf16 v[18:33], v[50:53], v[88:91], v[18:33]
	v_mfma_f32_32x32x16_bf16 v[2:17], v[54:57], v[88:91], v[2:17]
	ds_read_b128 v[50:53], v82
	ds_read_b128 v[54:57], v82 offset:4096
	ds_read_b128 v[88:91], v83
	s_waitcnt lgkmcnt(0)
	v_mfma_f32_32x32x16_bf16 v[18:33], v[50:53], v[88:91], v[18:33]
	v_mfma_f32_32x32x16_bf16 v[2:17], v[54:57], v[88:91], v[2:17]
	ds_read_b128 v[50:53], v84
	ds_read_b128 v[54:57], v84 offset:4096
	ds_read_b128 v[88:91], v85
	s_waitcnt lgkmcnt(0)
	v_mfma_f32_32x32x16_bf16 v[18:33], v[50:53], v[88:91], v[18:33]
	v_mfma_f32_32x32x16_bf16 v[2:17], v[54:57], v[88:91], v[2:17]
	ds_read_b128 v[50:53], v86
	ds_read_b128 v[54:57], v86 offset:4096
	ds_read_b128 v[88:91], v87
	s_waitcnt vmcnt(5)
	s_waitcnt lgkmcnt(0)
	s_barrier
	global_load_lds_dwordx4 v[48:49], off
	s_mov_b32 m0, s8
	s_waitcnt lgkmcnt(0)
	v_mfma_f32_32x32x16_bf16 v[18:33], v[50:53], v[88:91], v[18:33]
	global_load_lds_dwordx4 v[46:47], off
	s_mov_b32 m0, s16
	s_nop 0
	global_load_lds_dwordx4 v[38:39], off
	s_mov_b32 m0, s3
	v_mfma_f32_32x32x16_bf16 v[2:17], v[54:57], v[88:91], v[2:17]
	global_load_lds_dwordx4 v[36:37], off
	s_mov_b32 m0, s15
	s_nop 0
	global_load_lds_dwordx4 v[40:41], off
	ds_read_b128 v[40:43], v62 offset:32768
	ds_read_b128 v[50:53], v62 offset:36864
	ds_read_b128 v[54:57], v63
	s_waitcnt lgkmcnt(0)
	v_mfma_f32_32x32x16_bf16 v[18:33], v[40:43], v[54:57], v[18:33]
	s_mov_b32 m0, s53
	v_mfma_f32_32x32x16_bf16 v[2:17], v[50:53], v[54:57], v[2:17]
	ds_read_b128 v[40:43], v64 offset:32768
	ds_read_b128 v[50:53], v64 offset:36864
	ds_read_b128 v[54:57], v66
	s_waitcnt lgkmcnt(0)
	v_mfma_f32_32x32x16_bf16 v[18:33], v[40:43], v[54:57], v[18:33]
	v_mfma_f32_32x32x16_bf16 v[2:17], v[50:53], v[54:57], v[2:17]
	ds_read_b128 v[40:43], v68 offset:32768
	ds_read_b128 v[50:53], v68 offset:36864
	ds_read_b128 v[54:57], v69
	s_waitcnt lgkmcnt(0)
	v_mfma_f32_32x32x16_bf16 v[18:33], v[40:43], v[54:57], v[18:33]
	v_mfma_f32_32x32x16_bf16 v[2:17], v[50:53], v[54:57], v[2:17]
	ds_read_b128 v[40:43], v70 offset:32768
	ds_read_b128 v[50:53], v70 offset:36864
	ds_read_b128 v[54:57], v71
	s_waitcnt vmcnt(5)
	s_waitcnt lgkmcnt(0)
	s_barrier
;     ...
;       __builtin_amdgcn_s_barrier();
;       int buf = 0;
;       for (int kt = 0; kt < nk; ++kt) {
;         const int b2 = buf == 0 ? 2 : buf - 1;
;         if (kt + 2 < nk) issue(kt + 2, b2);
;         compute2(buf);
;         if (kt + 2 < nk) { if (BN == 128) asm volatile("s_waitcnt vmcnt(6)" ::: "memory"); else asm volatile("s_waitcnt vmcnt(5)" ::: "memory"); }
;         else asm volatile("s_waitcnt vmcnt(0)" ::: "memory");
;         asm volatile("s_waitcnt lgkmcnt(0)" ::: "memory");
;         __builtin_amdgcn_s_barrier();
;         buf = buf == 2 ? 0 : buf + 1;
;       }
	s_waitcnt lgkmcnt(0)
	v_mfma_f32_32x32x16_bf16 v[18:33], v[40:43], v[54:57], v[18:33]
	v_lshl_add_u64 v[40:41], v[48:49], 0, s[26:27]
	global_load_lds_dwordx4 v[40:41], off
	v_lshl_add_u64 v[40:41], v[46:47], 0, s[26:27]
	s_mov_b32 m0, s54
	v_readfirstlane_b32 s54, v80
	global_load_lds_dwordx4 v[40:41], off
	v_lshl_add_u64 v[40:41], v[38:39], 0, s[26:27]
	s_mov_b32 m0, s55
	v_mfma_f32_32x32x16_bf16 v[2:17], v[50:53], v[54:57], v[2:17]
	global_load_lds_dwordx4 v[40:41], off
	v_lshl_add_u64 v[40:41], v[36:37], 0, s[26:27]
	s_mov_b32 m0, s50
	s_nop 0
	global_load_lds_dwordx4 v[40:41], off
	v_lshl_add_u64 v[40:41], v[34:35], 0, s[56:57]
	s_mov_b32 m0, s51
	s_mov_b64 s[56:57], 0x600
	global_load_lds_dwordx4 v[40:41], off
	ds_read_b128 v[40:43], v75
	ds_read_b128 v[50:53], v75 offset:4096
	ds_read_b128 v[54:57], v63 offset:40960
	s_waitcnt lgkmcnt(0)
	v_mfma_f32_32x32x16_bf16 v[18:33], v[40:43], v[54:57], v[18:33]
	s_mov_b32 m0, s52
	s_mov_b64 s[52:53], 0x500
	v_mfma_f32_32x32x16_bf16 v[2:17], v[50:53], v[54:57], v[2:17]
	ds_read_b128 v[40:43], v77
	ds_read_b128 v[50:53], v77 offset:4096
	ds_read_b128 v[54:57], v66 offset:40960
	s_waitcnt lgkmcnt(0)
	v_mfma_f32_32x32x16_bf16 v[18:33], v[40:43], v[54:57], v[18:33]
	v_mfma_f32_32x32x16_bf16 v[2:17], v[50:53], v[54:57], v[2:17]
	ds_read_b128 v[40:43], v76
	ds_read_b128 v[50:53], v76 offset:4096
	ds_read_b128 v[54:57], v69 offset:40960
	s_waitcnt lgkmcnt(0)
	v_mfma_f32_32x32x16_bf16 v[18:33], v[40:43], v[54:57], v[18:33]
	v_mfma_f32_32x32x16_bf16 v[2:17], v[50:53], v[54:57], v[2:17]
	ds_read_b128 v[40:43], v74
	ds_read_b128 v[50:53], v74 offset:4096
	ds_read_b128 v[54:57], v71 offset:40960
	s_waitcnt vmcnt(5)
	s_waitcnt lgkmcnt(0)
	s_barrier
	s_waitcnt lgkmcnt(0)
	v_mfma_f32_32x32x16_bf16 v[18:33], v[40:43], v[54:57], v[18:33]
	v_lshl_add_u64 v[40:41], v[48:49], 0, s[90:91]
	global_load_lds_dwordx4 v[40:41], off
	v_lshl_add_u64 v[40:41], v[46:47], 0, s[90:91]
	s_mov_b32 m0, s14
	s_nop 0
	global_load_lds_dwordx4 v[40:41], off
	v_lshl_add_u64 v[40:41], v[38:39], 0, s[90:91]
	s_mov_b32 m0, s41
	v_mfma_f32_32x32x16_bf16 v[2:17], v[50:53], v[54:57], v[2:17]
	global_load_lds_dwordx4 v[40:41], off
	v_lshl_add_u64 v[40:41], v[36:37], 0, s[90:91]
	s_mov_b32 m0, s9
	s_nop 0
	global_load_lds_dwordx4 v[40:41], off
	v_lshl_add_u64 v[40:41], v[34:35], 0, s[52:53]
	s_mov_b32 m0, s40
	s_mov_b64 s[52:53], 0x580
	global_load_lds_dwordx4 v[40:41], off
	ds_read_b128 v[40:43], v79
	ds_read_b128 v[50:53], v79 offset:4096
	ds_read_b128 v[54:57], v81
	s_waitcnt lgkmcnt(0)
	v_mfma_f32_32x32x16_bf16 v[18:33], v[40:43], v[54:57], v[18:33]
	s_mov_b32 m0, s17
	v_mfma_f32_32x32x16_bf16 v[2:17], v[50:53], v[54:57], v[2:17]
	ds_read_b128 v[40:43], v82
	ds_read_b128 v[50:53], v82 offset:4096
	ds_read_b128 v[54:57], v83
	s_waitcnt lgkmcnt(0)
	v_mfma_f32_32x32x16_bf16 v[18:33], v[40:43], v[54:57], v[18:33]
	v_mfma_f32_32x32x16_bf16 v[2:17], v[50:53], v[54:57], v[2:17]
	ds_read_b128 v[40:43], v84
	ds_read_b128 v[50:53], v84 offset:4096
	ds_read_b128 v[54:57], v85
	s_waitcnt lgkmcnt(0)
	v_mfma_f32_32x32x16_bf16 v[18:33], v[40:43], v[54:57], v[18:33]
	v_mfma_f32_32x32x16_bf16 v[2:17], v[50:53], v[54:57], v[2:17]
	ds_read_b128 v[40:43], v86
	ds_read_b128 v[50:53], v86 offset:4096
	ds_read_b128 v[54:57], v87
	s_waitcnt vmcnt(5)
	s_waitcnt lgkmcnt(0)
	s_barrier
	s_waitcnt lgkmcnt(0)
	v_mfma_f32_32x32x16_bf16 v[18:33], v[40:43], v[54:57], v[18:33]
	v_lshl_add_u64 v[40:41], v[48:49], 0, s[38:39]
	global_load_lds_dwordx4 v[40:41], off
	v_lshl_add_u64 v[40:41], v[46:47], 0, s[38:39]
	s_mov_b32 m0, s8
	s_nop 0
	global_load_lds_dwordx4 v[40:41], off
	v_lshl_add_u64 v[40:41], v[38:39], 0, s[38:39]
	s_mov_b32 m0, s16
	v_mfma_f32_32x32x16_bf16 v[2:17], v[50:53], v[54:57], v[2:17]
	global_load_lds_dwordx4 v[40:41], off
	v_lshl_add_u64 v[40:41], v[36:37], 0, s[38:39]
	s_mov_b32 m0, s3
	s_nop 0
	global_load_lds_dwordx4 v[40:41], off
	v_lshl_add_u64 v[40:41], v[34:35], 0, s[52:53]
	s_mov_b32 m0, s15
	v_readfirstlane_b32 s53, v73
	global_load_lds_dwordx4 v[40:41], off
	ds_read_b128 v[40:43], v62 offset:32768
	ds_read_b128 v[50:53], v62 offset:36864
	ds_read_b128 v[54:57], v63
	s_waitcnt lgkmcnt(0)
	v_mfma_f32_32x32x16_bf16 v[18:33], v[40:43], v[54:57], v[18:33]
	s_mov_b32 m0, s53
	v_readfirstlane_b32 s52, v78
	v_mfma_f32_32x32x16_bf16 v[2:17], v[50:53], v[54:57], v[2:17]
	ds_read_b128 v[40:43], v64 offset:32768
	ds_read_b128 v[50:53], v64 offset:36864
	ds_read_b128 v[54:57], v66
	s_waitcnt lgkmcnt(0)
	v_mfma_f32_32x32x16_bf16 v[18:33], v[40:43], v[54:57], v[18:33]
	v_mfma_f32_32x32x16_bf16 v[2:17], v[50:53], v[54:57], v[2:17]
	ds_read_b128 v[40:43], v68 offset:32768
	ds_read_b128 v[50:53], v68 offset:36864
	ds_read_b128 v[54:57], v69
	s_waitcnt lgkmcnt(0)
	v_mfma_f32_32x32x16_bf16 v[18:33], v[40:43], v[54:57], v[18:33]
	v_mfma_f32_32x32x16_bf16 v[2:17], v[50:53], v[54:57], v[2:17]
	ds_read_b128 v[40:43], v70 offset:32768
	ds_read_b128 v[50:53], v70 offset:36864
	ds_read_b128 v[54:57], v71
	s_waitcnt vmcnt(5)
	s_waitcnt lgkmcnt(0)
	s_barrier
;     ...
;       __builtin_amdgcn_s_barrier();
;       int buf = 0;
;       for (int kt = 0; kt < nk; ++kt) {
;         const int b2 = buf == 0 ? 2 : buf - 1;
;         if (kt + 2 < nk) issue(kt + 2, b2);
;         compute2(buf);
;         if (kt + 2 < nk) { if (BN == 128) asm volatile("s_waitcnt vmcnt(6)" ::: "memory"); else asm volatile("s_waitcnt vmcnt(5)" ::: "memory"); }
;         else asm volatile("s_waitcnt vmcnt(0)" ::: "memory");
;         asm volatile("s_waitcnt lgkmcnt(0)" ::: "memory");
;         __builtin_amdgcn_s_barrier();
;         buf = buf == 2 ? 0 : buf + 1;
;       }
	s_waitcnt lgkmcnt(0)
	v_mfma_f32_32x32x16_bf16 v[18:33], v[40:43], v[54:57], v[18:33]
	v_lshl_add_u64 v[40:41], v[48:49], 0, s[34:35]
	global_load_lds_dwordx4 v[40:41], off
	v_lshl_add_u64 v[40:41], v[46:47], 0, s[34:35]
	s_mov_b32 m0, s52
	s_nop 0
	global_load_lds_dwordx4 v[40:41], off
	v_lshl_add_u64 v[40:41], v[38:39], 0, s[34:35]
	s_mov_b32 m0, s54
	v_mfma_f32_32x32x16_bf16 v[2:17], v[50:53], v[54:57], v[2:17]
	global_load_lds_dwordx4 v[40:41], off
	v_lshl_add_u64 v[40:41], v[36:37], 0, s[34:35]
	s_mov_b32 m0, s50
	v_readfirstlane_b32 s50, v72
	global_load_lds_dwordx4 v[40:41], off
	v_lshl_add_u64 v[40:41], v[34:35], 0, s[56:57]
	s_mov_b32 m0, s51
	s_nop 0
	global_load_lds_dwordx4 v[40:41], off
	ds_read_b128 v[40:43], v75
	ds_read_b128 v[50:53], v75 offset:4096
	ds_read_b128 v[54:57], v63 offset:40960
	s_waitcnt lgkmcnt(0)
	v_mfma_f32_32x32x16_bf16 v[18:33], v[40:43], v[54:57], v[18:33]
	s_mov_b32 m0, s50
	s_mov_b64 s[50:51], 0x680
	v_mfma_f32_32x32x16_bf16 v[2:17], v[50:53], v[54:57], v[2:17]
	ds_read_b128 v[40:43], v77
	ds_read_b128 v[50:53], v77 offset:4096
	ds_read_b128 v[54:57], v66 offset:40960
	s_waitcnt lgkmcnt(0)
	v_mfma_f32_32x32x16_bf16 v[18:33], v[40:43], v[54:57], v[18:33]
	v_mfma_f32_32x32x16_bf16 v[2:17], v[50:53], v[54:57], v[2:17]
	ds_read_b128 v[40:43], v76
	ds_read_b128 v[50:53], v76 offset:4096
	ds_read_b128 v[54:57], v69 offset:40960
	s_waitcnt lgkmcnt(0)
	v_mfma_f32_32x32x16_bf16 v[18:33], v[40:43], v[54:57], v[18:33]
	v_mfma_f32_32x32x16_bf16 v[2:17], v[50:53], v[54:57], v[2:17]
	ds_read_b128 v[40:43], v74
	ds_read_b128 v[50:53], v74 offset:4096
	ds_read_b128 v[54:57], v71 offset:40960
	s_waitcnt vmcnt(5)
	s_waitcnt lgkmcnt(0)
	s_barrier
	s_waitcnt lgkmcnt(0)
	v_mfma_f32_32x32x16_bf16 v[18:33], v[40:43], v[54:57], v[18:33]
	v_lshl_add_u64 v[40:41], v[48:49], 0, s[22:23]
	global_load_lds_dwordx4 v[40:41], off
	v_lshl_add_u64 v[40:41], v[46:47], 0, s[22:23]
	s_mov_b32 m0, s14
	s_nop 0
	global_load_lds_dwordx4 v[40:41], off
	v_lshl_add_u64 v[40:41], v[38:39], 0, s[22:23]
	s_mov_b32 m0, s41
	v_mfma_f32_32x32x16_bf16 v[2:17], v[50:53], v[54:57], v[2:17]
	global_load_lds_dwordx4 v[40:41], off
	v_lshl_add_u64 v[40:41], v[36:37], 0, s[22:23]
	s_mov_b32 m0, s9
	s_nop 0
	global_load_lds_dwordx4 v[40:41], off
	v_lshl_add_u64 v[40:41], v[34:35], 0, s[50:51]
	s_mov_b32 m0, s40
	s_nop 0
	global_load_lds_dwordx4 v[40:41], off
	ds_read_b128 v[40:43], v79
	ds_read_b128 v[50:53], v79 offset:4096
	ds_read_b128 v[54:57], v81
	s_waitcnt lgkmcnt(0)
	v_mfma_f32_32x32x16_bf16 v[18:33], v[40:43], v[54:57], v[18:33]
	s_mov_b32 m0, s17
	v_mfma_f32_32x32x16_bf16 v[2:17], v[50:53], v[54:57], v[2:17]
	ds_read_b128 v[40:43], v82
	ds_read_b128 v[50:53], v82 offset:4096
	ds_read_b128 v[54:57], v83
	s_waitcnt lgkmcnt(0)
	v_mfma_f32_32x32x16_bf16 v[18:33], v[40:43], v[54:57], v[18:33]
	v_mfma_f32_32x32x16_bf16 v[2:17], v[50:53], v[54:57], v[2:17]
	ds_read_b128 v[40:43], v84
	ds_read_b128 v[50:53], v84 offset:4096
	ds_read_b128 v[54:57], v85
	s_waitcnt lgkmcnt(0)
	v_mfma_f32_32x32x16_bf16 v[18:33], v[40:43], v[54:57], v[18:33]
	v_mfma_f32_32x32x16_bf16 v[2:17], v[50:53], v[54:57], v[2:17]
	ds_read_b128 v[40:43], v86
	ds_read_b128 v[50:53], v86 offset:4096
	ds_read_b128 v[54:57], v87
	s_waitcnt vmcnt(5)
	s_waitcnt lgkmcnt(0)
	s_barrier
	s_waitcnt lgkmcnt(0)
	v_mfma_f32_32x32x16_bf16 v[18:33], v[40:43], v[54:57], v[18:33]
	v_lshl_add_u64 v[40:41], v[48:49], 0, s[6:7]
	global_load_lds_dwordx4 v[40:41], off
	v_lshl_add_u64 v[40:41], v[46:47], 0, s[6:7]
	s_mov_b32 m0, s8
	s_mov_b64 s[8:9], 0x700
	global_load_lds_dwordx4 v[40:41], off
	v_lshl_add_u64 v[40:41], v[38:39], 0, s[6:7]
	s_mov_b32 m0, s16
	v_mfma_f32_32x32x16_bf16 v[2:17], v[50:53], v[54:57], v[2:17]
	global_load_lds_dwordx4 v[40:41], off
	v_lshl_add_u64 v[40:41], v[36:37], 0, s[6:7]
	s_mov_b32 m0, s3
	v_lshl_add_u64 v[38:39], v[38:39], 0, s[58:59]
	global_load_lds_dwordx4 v[40:41], off
	v_lshl_add_u64 v[40:41], v[34:35], 0, s[8:9]
	s_mov_b32 m0, s15
	v_readfirstlane_b32 s3, v65
	global_load_lds_dwordx4 v[40:41], off
	ds_read_b128 v[40:43], v62 offset:32768
	ds_read_b128 v[50:53], v62 offset:36864
	ds_read_b128 v[54:57], v63
	s_waitcnt lgkmcnt(0)
	v_mfma_f32_32x32x16_bf16 v[18:33], v[40:43], v[54:57], v[18:33]
	s_mov_b32 m0, s53
	v_lshl_add_u64 v[36:37], v[36:37], 0, s[58:59]
	s_mov_b64 s[8:9], 0x780
	v_lshl_add_u64 v[34:35], v[34:35], 0, s[8:9]
	v_mfma_f32_32x32x16_bf16 v[2:17], v[50:53], v[54:57], v[2:17]
	ds_read_b128 v[40:43], v64 offset:32768
	ds_read_b128 v[50:53], v64 offset:36864
	ds_read_b128 v[54:57], v66
	s_waitcnt lgkmcnt(0)
	v_mfma_f32_32x32x16_bf16 v[18:33], v[40:43], v[54:57], v[18:33]
	v_mfma_f32_32x32x16_bf16 v[2:17], v[50:53], v[54:57], v[2:17]
	ds_read_b128 v[40:43], v68 offset:32768
	ds_read_b128 v[50:53], v68 offset:36864
	ds_read_b128 v[54:57], v69
	s_waitcnt lgkmcnt(0)
	v_mfma_f32_32x32x16_bf16 v[18:33], v[40:43], v[54:57], v[18:33]
	v_mfma_f32_32x32x16_bf16 v[2:17], v[50:53], v[54:57], v[2:17]
	ds_read_b128 v[40:43], v70 offset:32768
	ds_read_b128 v[50:53], v70 offset:36864
	ds_read_b128 v[54:57], v71
	s_waitcnt vmcnt(5)
	s_waitcnt lgkmcnt(0)
	s_barrier
;     ...
;       for (int kt = 0; kt < nk; ++kt) {
;         const int b2 = buf == 0 ? 2 : buf - 1;
;         if (kt + 2 < nk) issue(kt + 2, b2);
;         compute2(buf);
;         if (kt + 2 < nk) { if (BN == 128) asm volatile("s_waitcnt vmcnt(6)" ::: "memory"); else asm volatile("s_waitcnt vmcnt(5)" ::: "memory"); }
;         else asm volatile("s_waitcnt vmcnt(0)" ::: "memory");
;         asm volatile("s_waitcnt lgkmcnt(0)" ::: "memory");
;         __builtin_amdgcn_s_barrier();
;         buf = buf == 2 ? 0 : buf + 1;
;       }
;     } else {
;       if (!(chain & 1)) {
;         issue(0, 0);
;         asm volatile("s_waitcnt vmcnt(0)" ::: "memory");
;         __syncthreads();
;       }
;       for (int kt = 0; kt < nk; ++kt) {
;         const int buf = kt & 1;
;         if (kt + 1 < nk) issue(kt + 1, buf ^ 1);
;         else if (chain & 2) issue_at(nmt * 256, nnt * BN, 0, buf ^ 1);
;         compute2(buf);
;         asm volatile("s_waitcnt vmcnt(0)" ::: "memory");
;         __syncthreads();
;       }
;     }
;     __syncthreads();
	s_waitcnt lgkmcnt(0)
	v_mfma_f32_32x32x16_bf16 v[18:33], v[40:43], v[54:57], v[18:33]
	v_lshl_add_u64 v[40:41], v[48:49], 0, s[58:59]
	global_load_lds_dwordx4 v[40:41], off
	v_lshl_add_u64 v[40:41], v[46:47], 0, s[58:59]
	s_mov_b32 m0, s52
	s_nop 0
	global_load_lds_dwordx4 v[40:41], off
	s_mov_b32 m0, s54
	v_mfma_f32_32x32x16_bf16 v[2:17], v[50:53], v[54:57], v[2:17]
	global_load_lds_dwordx4 v[38:39], off
	s_mov_b32 m0, s3
	v_readfirstlane_b32 s3, v67
	global_load_lds_dwordx4 v[36:37], off
	s_mov_b32 m0, s3
	s_ashr_i32 s3, s2, 31
	global_load_lds_dwordx4 v[34:35], off
	ds_read_b128 v[34:37], v75
	ds_read_b128 v[38:41], v75 offset:4096
	ds_read_b128 v[42:45], v63 offset:40960
	s_waitcnt lgkmcnt(0)
	v_mfma_f32_32x32x16_bf16 v[18:33], v[34:37], v[42:45], v[18:33]
	v_mfma_f32_32x32x16_bf16 v[2:17], v[38:41], v[42:45], v[2:17]
	ds_read_b128 v[34:37], v77
	ds_read_b128 v[38:41], v77 offset:4096
	ds_read_b128 v[42:45], v66 offset:40960
	s_waitcnt lgkmcnt(0)
	v_mfma_f32_32x32x16_bf16 v[18:33], v[34:37], v[42:45], v[18:33]
	v_mfma_f32_32x32x16_bf16 v[2:17], v[38:41], v[42:45], v[2:17]
	ds_read_b128 v[34:37], v76
	ds_read_b128 v[38:41], v76 offset:4096
	ds_read_b128 v[42:45], v69 offset:40960
	s_waitcnt lgkmcnt(0)
	v_mfma_f32_32x32x16_bf16 v[18:33], v[34:37], v[42:45], v[18:33]
	v_mfma_f32_32x32x16_bf16 v[2:17], v[38:41], v[42:45], v[2:17]
	ds_read_b128 v[34:37], v74
	ds_read_b128 v[38:41], v74 offset:4096
	ds_read_b128 v[42:45], v71 offset:40960
	s_waitcnt vmcnt(5)
	s_waitcnt lgkmcnt(0)
	s_barrier
	s_waitcnt lgkmcnt(0)
	v_mfma_f32_32x32x16_bf16 v[18:33], v[34:37], v[42:45], v[18:33]
	v_mfma_f32_32x32x16_bf16 v[2:17], v[38:41], v[42:45], v[2:17]
	ds_read_b128 v[34:37], v87
	ds_read_b128 v[38:41], v86 offset:4096
	ds_read_b128 v[42:45], v86
	ds_read_b128 v[46:49], v85
	ds_read_b128 v[50:53], v84 offset:4096
	ds_read_b128 v[54:57], v84
	ds_read_b128 v[72:75], v83
	ds_read_b128 v[84:87], v82 offset:4096
	ds_read_b128 v[88:91], v82
	ds_read_b128 v[80:83], v81
	ds_read_b128 v[92:95], v79 offset:4096
	ds_read_b128 v[76:79], v79
	s_waitcnt vmcnt(0)
	s_waitcnt lgkmcnt(0)
	s_barrier
	s_waitcnt lgkmcnt(0)
	v_mfma_f32_32x32x16_bf16 v[18:33], v[76:79], v[80:83], v[18:33]
	v_mfma_f32_32x32x16_bf16 v[2:17], v[92:95], v[80:83], v[2:17]
	v_mfma_f32_32x32x16_bf16 v[18:33], v[88:91], v[72:75], v[18:33]
	v_mfma_f32_32x32x16_bf16 v[2:17], v[84:87], v[72:75], v[2:17]
	v_mfma_f32_32x32x16_bf16 v[18:33], v[54:57], v[46:49], v[18:33]
	v_mfma_f32_32x32x16_bf16 v[2:17], v[50:53], v[46:49], v[2:17]
	v_mfma_f32_32x32x16_bf16 v[18:33], v[42:45], v[34:37], v[18:33]
	v_mfma_f32_32x32x16_bf16 v[2:17], v[38:41], v[34:37], v[2:17]
	ds_read_b128 v[34:37], v71
	ds_read_b128 v[38:41], v70 offset:36864
	ds_read_b128 v[42:45], v70 offset:32768
	ds_read_b128 v[46:49], v69
	ds_read_b128 v[50:53], v68 offset:36864
	ds_read_b128 v[54:57], v68 offset:32768
	ds_read_b128 v[66:69], v66
	ds_read_b128 v[70:73], v64 offset:36864
	ds_read_b128 v[74:77], v64 offset:32768
	ds_read_b128 v[78:81], v63
	ds_read_b128 v[82:85], v62 offset:36864
	ds_read_b128 v[62:65], v62 offset:32768
	s_waitcnt vmcnt(0)
	s_waitcnt lgkmcnt(0)
	s_barrier
	s_waitcnt vmcnt(0) lgkmcnt(0)
	s_barrier
; DI unsigned pack2(float a, float b) { fl2_t f; f.x = a; f.y = b; bf16x2_t r = __builtin_convertvector(f, bf16x2_t); return __builtin_bit_cast(unsigned, r); }
; DI float bflo(unsigned u) { return __uint_as_float(u << 16); }
; DI float bfhi(unsigned u) { return __uint_as_float(u & 0xffff0000u); }
; DI float sigmoidf_(float x) { return __builtin_amdgcn_rcpf(1.f + __expf(-x)); }
; DI void store4(u16* dst, float a, float b, float c, float d) { *(uint2*)dst = make_uint2(pack2(a, b), pack2(c, d)); }
;     ...
;   const int nw = n0 + wn * 64;
; #pragma unroll
;   for (int i = 0; i < MI; ++i) {
;     const int m = m0 + wm * (MI * 32) + i * 32 + l32;
;     if (EPI == EPI_UP) {
;       const float rs = rsl[m - m0];
;       const int hb0 = nw >> 1;
; #pragma unroll
;       for (int gq = 0; gq < 4; ++gq) {
;         float v[4];
; #pragma unroll
;         for (int r = 0; r < 4; ++r) {
;           float gt = acc[i][0][4 * gq + r] * rs, up = acc[i][1][4 * gq + r] * rs;
;           v[r] = gt * sigmoidf_(gt) * up;
;         }
;         int hid = hb0 + 8 * gq + 4 * hh;
;         u16* dst = hid < 1408 ? p.regB + (size_t)m * 1408 + hid : (u16*)p.out + (size_t)m * 1408 + (hid - 1408);
;         store4(dst, v[0], v[1], v[2], v[3]);
;       }
;     } else if (EPI == EPI_RES) {
;       float ss = 0.f;
; #pragma unroll
;       for (int j = 0; j < 2; ++j)
; #pragma unroll
;         for (int gq = 0; gq < 4; ++gq) {
;           u16* hp = p.hb + (size_t)m * 1024 + nw + j * 32 + 8 * gq + 4 * hh;
;           uint2 old = *(const uint2*)hp;
;           float h0 = bflo(old.x) + g.scale * acc[i][j][4 * gq + 0];
;           float h1 = bfhi(old.x) + g.scale * acc[i][j][4 * gq + 1];
;           float h2 = bflo(old.y) + g.scale * acc[i][j][4 * gq + 2];
;           float h3 = bfhi(old.y) + g.scale * acc[i][j][4 * gq + 3];
;           unsigned p0 = pack2(h0, h1), p1 = pack2(h2, h3);
;           *(uint2*)hp = make_uint2(p0, p1);
;           float r0 = bflo(p0), r1 = bfhi(p0), r2 = bflo(p1), r3 = bfhi(p1);
;           ss += r0 * r0 + r1 * r1 + r2 * r2 + r3 * r3;
;         }
;       ss += __shfl_xor(ss, 32);
;       if (hh == 0) p.ssq[(size_t)(nw >> 6) * TP + m] = ss;
	v_mfma_f32_32x32x16_bf16 v[18:33], v[62:65], v[78:81], v[18:33]
	v_mfma_f32_32x32x16_bf16 v[2:17], v[82:85], v[78:81], v[2:17]
	v_mfma_f32_32x32x16_bf16 v[18:33], v[74:77], v[66:69], v[18:33]
	v_mfma_f32_32x32x16_bf16 v[2:17], v[70:73], v[66:69], v[2:17]
	v_mfma_f32_32x32x16_bf16 v[18:33], v[54:57], v[46:49], v[18:33]
	v_mfma_f32_32x32x16_bf16 v[2:17], v[50:53], v[46:49], v[2:17]
	v_mfma_f32_32x32x16_bf16 v[18:33], v[42:45], v[34:37], v[18:33]
	v_mfma_f32_32x32x16_bf16 v[2:17], v[38:41], v[34:37], v[2:17]
	v_or_b32_e32 v34, v61, v60
	v_ashrrev_i32_e32 v35, 31, v34
	v_lshlrev_b64 v[36:37], 11, v[34:35]
	v_lshl_add_u64 v[36:37], s[44:45], 0, v[36:37]
	v_lshl_add_u64 v[36:37], s[2:3], 1, v[36:37]
	v_and_b32_e32 v38, 64, v183
	v_lshl_add_u64 v[36:37], v[36:37], 0, v[0:1]
	v_xor_b32_e32 v0, 32, v183
	v_add_u32_e32 v38, 64, v38
	v_cmp_lt_i32_e32 vcc, v0, v38
	global_load_dwordx2 v[204:205], v[36:37], off
	global_load_dwordx2 v[206:207], v[36:37], off offset:16
	global_load_dwordx2 v[208:209], v[36:37], off offset:32
	global_load_dwordx2 v[210:211], v[36:37], off offset:48
	global_load_dwordx2 v[212:213], v[36:37], off offset:64
	global_load_dwordx2 v[214:215], v[36:37], off offset:80
	global_load_dwordx2 v[216:217], v[36:37], off offset:96
	global_load_dwordx2 v[218:219], v[36:37], off offset:112
	s_waitcnt vmcnt(7)
	v_lshlrev_b32_e32 v40, 16, v204
	v_and_b32_e32 v41, 0xffff0000, v204
	v_lshlrev_b32_e32 v38, 16, v205
	v_and_b32_e32 v39, 0xffff0000, v205
	v_pk_add_f32 v[18:19], v[18:19], v[40:41]
	v_pk_add_f32 v[20:21], v[20:21], v[38:39]
	v_cvt_pk_bf16_f32 v18, v18, v19
	v_cvt_pk_bf16_f32 v19, v20, v21
	global_store_dwordx2 v[36:37], v[18:19], off
	v_lshlrev_b32_e32 v20, 16, v18
	v_and_b32_e32 v18, 0xffff0000, v18
	v_mul_f32_e32 v38, v18, v18
	v_lshlrev_b32_e32 v21, 16, v19
	v_fmac_f32_e32 v38, v20, v20
	v_and_b32_e32 v19, 0xffff0000, v19
	v_fmac_f32_e32 v38, v21, v21
	v_fmac_f32_e32 v38, v19, v19
	v_cndmask_b32_e32 v0, v183, v0, vcc
	v_lshlrev_b32_e32 v0, 2, v0
	v_cmp_gt_u32_e32 vcc, 32, v58
	s_waitcnt vmcnt(7)
	v_lshlrev_b32_e32 v20, 16, v206
	v_and_b32_e32 v21, 0xffff0000, v206
	v_pk_add_f32 v[20:21], v[22:23], v[20:21]
	v_lshlrev_b32_e32 v18, 16, v207
	v_and_b32_e32 v19, 0xffff0000, v207
	v_pk_add_f32 v[18:19], v[24:25], v[18:19]
	v_cvt_pk_bf16_f32 v20, v20, v21
	v_cvt_pk_bf16_f32 v21, v18, v19
	v_and_b32_e32 v19, 0xffff0000, v20
	v_lshlrev_b32_e32 v18, 16, v20
	v_mul_f32_e32 v19, v19, v19
	global_store_dwordx2 v[36:37], v[20:21], off offset:16
	v_lshlrev_b32_e32 v20, 16, v21
	v_fmac_f32_e32 v19, v18, v18
	v_and_b32_e32 v21, 0xffff0000, v21
	v_fmac_f32_e32 v19, v20, v20
	v_fmac_f32_e32 v19, v21, v21
	v_add_f32_e32 v22, v38, v19
	s_waitcnt vmcnt(7)
	v_lshlrev_b32_e32 v20, 16, v208
	v_and_b32_e32 v21, 0xffff0000, v208
	v_pk_add_f32 v[20:21], v[26:27], v[20:21]
	v_lshlrev_b32_e32 v18, 16, v209
	v_and_b32_e32 v19, 0xffff0000, v209
	v_pk_add_f32 v[18:19], v[28:29], v[18:19]
	v_cvt_pk_bf16_f32 v20, v20, v21
	v_cvt_pk_bf16_f32 v21, v18, v19
	v_and_b32_e32 v19, 0xffff0000, v20
	v_lshlrev_b32_e32 v18, 16, v20
	v_mul_f32_e32 v19, v19, v19
	global_store_dwordx2 v[36:37], v[20:21], off offset:32
	v_lshlrev_b32_e32 v20, 16, v21
	v_fmac_f32_e32 v19, v18, v18
	v_and_b32_e32 v21, 0xffff0000, v21
	v_fmac_f32_e32 v19, v20, v20
	v_fmac_f32_e32 v19, v21, v21
	v_add_f32_e32 v22, v22, v19
	s_waitcnt vmcnt(7)
	v_lshlrev_b32_e32 v20, 16, v210
	v_and_b32_e32 v21, 0xffff0000, v210
	v_pk_add_f32 v[20:21], v[30:31], v[20:21]
	v_lshlrev_b32_e32 v18, 16, v211
	v_and_b32_e32 v19, 0xffff0000, v211
	v_pk_add_f32 v[18:19], v[32:33], v[18:19]
	v_cvt_pk_bf16_f32 v20, v20, v21
	v_cvt_pk_bf16_f32 v21, v18, v19
	v_and_b32_e32 v19, 0xffff0000, v20
	v_lshlrev_b32_e32 v18, 16, v20
	v_mul_f32_e32 v19, v19, v19
	global_store_dwordx2 v[36:37], v[20:21], off offset:48
	v_lshlrev_b32_e32 v20, 16, v21
	v_fmac_f32_e32 v19, v18, v18
	v_and_b32_e32 v21, 0xffff0000, v21
	v_fmac_f32_e32 v19, v20, v20
	v_fmac_f32_e32 v19, v21, v21
	v_add_f32_e32 v22, v22, v19
	s_waitcnt vmcnt(7)
	v_lshlrev_b32_e32 v20, 16, v212
	v_and_b32_e32 v21, 0xffff0000, v212
	v_lshlrev_b32_e32 v18, 16, v213
	v_and_b32_e32 v19, 0xffff0000, v213
	v_pk_add_f32 v[2:3], v[2:3], v[20:21]
	v_pk_add_f32 v[4:5], v[4:5], v[18:19]
	v_cvt_pk_bf16_f32 v2, v2, v3
	v_cvt_pk_bf16_f32 v3, v4, v5
	global_store_dwordx2 v[36:37], v[2:3], off offset:64
	v_lshlrev_b32_e32 v4, 16, v2
	v_and_b32_e32 v2, 0xffff0000, v2
	v_mul_f32_e32 v2, v2, v2
	v_lshlrev_b32_e32 v5, 16, v3
	v_fmac_f32_e32 v2, v4, v4
	v_and_b32_e32 v3, 0xffff0000, v3
	v_fmac_f32_e32 v2, v5, v5
	v_fmac_f32_e32 v2, v3, v3
	v_add_f32_e32 v18, v22, v2
	s_waitcnt vmcnt(7)
	v_lshlrev_b32_e32 v4, 16, v214
	v_and_b32_e32 v5, 0xffff0000, v214
	v_pk_add_f32 v[4:5], v[6:7], v[4:5]
	v_lshlrev_b32_e32 v2, 16, v215
	v_and_b32_e32 v3, 0xffff0000, v215
	v_pk_add_f32 v[2:3], v[8:9], v[2:3]
	v_cvt_pk_bf16_f32 v4, v4, v5
	v_cvt_pk_bf16_f32 v5, v2, v3
	v_and_b32_e32 v3, 0xffff0000, v4
	v_lshlrev_b32_e32 v2, 16, v4
	v_mul_f32_e32 v3, v3, v3
	global_store_dwordx2 v[36:37], v[4:5], off offset:80
	v_lshlrev_b32_e32 v4, 16, v5
	v_fmac_f32_e32 v3, v2, v2
	v_and_b32_e32 v5, 0xffff0000, v5
	v_fmac_f32_e32 v3, v4, v4
	v_fmac_f32_e32 v3, v5, v5
	v_add_f32_e32 v6, v18, v3
	s_waitcnt vmcnt(7)
	v_lshlrev_b32_e32 v4, 16, v216
	v_and_b32_e32 v5, 0xffff0000, v216
	v_pk_add_f32 v[4:5], v[10:11], v[4:5]
	v_lshlrev_b32_e32 v2, 16, v217
	v_and_b32_e32 v3, 0xffff0000, v217
	v_pk_add_f32 v[2:3], v[12:13], v[2:3]
	v_cvt_pk_bf16_f32 v4, v4, v5
	v_cvt_pk_bf16_f32 v5, v2, v3
	v_and_b32_e32 v3, 0xffff0000, v4
	v_lshlrev_b32_e32 v2, 16, v4
	v_mul_f32_e32 v3, v3, v3
	global_store_dwordx2 v[36:37], v[4:5], off offset:96
	v_lshlrev_b32_e32 v4, 16, v5
	v_fmac_f32_e32 v3, v2, v2
	v_and_b32_e32 v5, 0xffff0000, v5
	v_fmac_f32_e32 v3, v4, v4
	v_fmac_f32_e32 v3, v5, v5
	v_add_f32_e32 v6, v6, v3
	s_waitcnt vmcnt(7)
	v_lshlrev_b32_e32 v4, 16, v218
	v_and_b32_e32 v5, 0xffff0000, v218
	v_pk_add_f32 v[4:5], v[14:15], v[4:5]
	v_lshlrev_b32_e32 v2, 16, v219
	v_and_b32_e32 v3, 0xffff0000, v219
	v_pk_add_f32 v[2:3], v[16:17], v[2:3]
	v_cvt_pk_bf16_f32 v4, v4, v5
	v_cvt_pk_bf16_f32 v5, v2, v3
	v_and_b32_e32 v3, 0xffff0000, v4
	v_lshlrev_b32_e32 v2, 16, v4
	v_mul_f32_e32 v3, v3, v3
	global_store_dwordx2 v[36:37], v[4:5], off offset:112
	v_lshlrev_b32_e32 v4, 16, v5
	v_fmac_f32_e32 v3, v2, v2
	v_and_b32_e32 v5, 0xffff0000, v5
	v_fmac_f32_e32 v3, v4, v4
	v_fmac_f32_e32 v3, v5, v5
	v_add_f32_e32 v2, v6, v3
	ds_bpermute_b32 v0, v0, v2
	s_and_saveexec_b64 s[8:9], vcc
	s_cbranch_execz .LBB0_59
	s_mul_i32 s14, s10, 0x20400
	s_mul_hi_i32 s3, s10, 0x20400
	s_add_u32 s14, s42, s14
	s_addc_u32 s15, s43, s3
	v_lshl_add_u64 v[4:5], v[34:35], 2, s[14:15]
	s_waitcnt lgkmcnt(0)
	v_add_f32_e32 v0, v2, v0
	global_store_dword v[4:5], v0, off
	s_branch .LBB0_59

; #define MFMA(a, b, c) __builtin_amdgcn_mfma_f32_32x32x16_bf16((a), (b), (c), 0, 0, 0)
; DI unsigned pack2(float a, float b) { fl2_t f; f.x = a; f.y = b; bf16x2_t r = __builtin_convertvector(f, bf16x2_t); return __builtin_bit_cast(unsigned, r); }
; DI float bflo(unsigned u) { return __uint_as_float(u << 16); }
; DI float bfhi(unsigned u) { return __uint_as_float(u & 0xffff0000u); }
;     ...
;     auto compute2 = [&](int buf) {
;       const char* lb = L0 + buf * BUFB;
; #pragma unroll
;       for (int ks = 0; ks < 4; ++ks) {
;         const int c = ks * 2 + hh;
;         bf16x8 wf[2], xf[MI];
; #pragma unroll
;         for (int j = 0; j < 2; ++j) { const int r = wn * 64 + j * 32 + l32; wf[j] = *(const bf16x8*)(lb + 256 * 128 + r * 128 + ((c ^ ((r >> 1) & 7)) << 4)); }
; #pragma unroll
;         for (int i = 0; i < MI; ++i) { const int r = wm * (MI * 32) + i * 32 + l32; xf[i] = *(const bf16x8*)(lb + r * 128 + ((c ^ ((r >> 1) & 7)) << 4)); }
; #pragma unroll
;         for (int i = 0; i < MI; ++i) {
;           acc[i][0] = MFMA(wf[0], xf[i], acc[i][0]);
;           acc[i][1] = MFMA(wf[1], xf[i], acc[i][1]);
;         }
;       }
;     };
;     ...
;     } else if (EPI == EPI_RES) {
;       float ss = 0.f;
; #pragma unroll
;       for (int j = 0; j < 2; ++j)
; #pragma unroll
;         for (int gq = 0; gq < 4; ++gq) {
;           u16* hp = p.hb + (size_t)m * 1024 + nw + j * 32 + 8 * gq + 4 * hh;
;           uint2 old = *(const uint2*)hp;
;           float h0 = bflo(old.x) + g.scale * acc[i][j][4 * gq + 0];
;           float h1 = bfhi(old.x) + g.scale * acc[i][j][4 * gq + 1];
;           float h2 = bflo(old.y) + g.scale * acc[i][j][4 * gq + 2];
;           float h3 = bfhi(old.y) + g.scale * acc[i][j][4 * gq + 3];
;           unsigned p0 = pack2(h0, h1), p1 = pack2(h2, h3);
;           *(uint2*)hp = make_uint2(p0, p1);
;           float r0 = bflo(p0), r1 = bfhi(p0), r2 = bflo(p1), r3 = bfhi(p1);
;           ss += r0 * r0 + r1 * r1 + r2 * r2 + r3 * r3;
;         }
;       ss += __shfl_xor(ss, 32);
;       if (hh == 0) p.ssq[(size_t)(nw >> 6) * TP + m] = ss;
.LBB0_1277:
	v_add3_u32 v0, s25, v201, v175
	ds_read_b128 v[130:133], v0
	ds_read_b128 v[134:137], v0 offset:4096
	v_add3_u32 v0, s24, v201, v174
	ds_read_b128 v[138:141], v0
	ds_read_b128 v[142:145], v0 offset:4096
	ds_read_b128 v[146:149], v0 offset:8192
	ds_read_b128 v[150:153], v0 offset:12288
	v_add3_u32 v0, s25, v200, v175
	s_waitcnt lgkmcnt(0)
	v_mfma_f32_32x32x16_bf16 v[114:129], v[130:133], v[138:141], v[114:129]
	s_mov_b32 s2, 0x20400
	v_mfma_f32_32x32x16_bf16 v[98:113], v[134:137], v[138:141], v[98:113]
	v_mfma_f32_32x32x16_bf16 v[66:81], v[134:137], v[142:145], v[66:81]
	v_mfma_f32_32x32x16_bf16 v[34:49], v[134:137], v[146:149], v[34:49]
	v_mfma_f32_32x32x16_bf16 v[2:17], v[134:137], v[150:153], v[2:17]
	v_mfma_f32_32x32x16_bf16 v[82:97], v[130:133], v[142:145], v[82:97]
	v_mfma_f32_32x32x16_bf16 v[50:65], v[130:133], v[146:149], v[50:65]
	v_mfma_f32_32x32x16_bf16 v[18:33], v[130:133], v[150:153], v[18:33]
	ds_read_b128 v[130:133], v0
	ds_read_b128 v[134:137], v0 offset:4096
	v_add3_u32 v0, s24, v200, v174
	ds_read_b128 v[138:141], v0
	ds_read_b128 v[142:145], v0 offset:4096
	ds_read_b128 v[146:149], v0 offset:8192
	ds_read_b128 v[150:153], v0 offset:12288
	v_add3_u32 v0, s25, v199, v175
	s_waitcnt lgkmcnt(0)
	v_mfma_f32_32x32x16_bf16 v[98:113], v[134:137], v[138:141], v[98:113]
	v_mfma_f32_32x32x16_bf16 v[66:81], v[134:137], v[142:145], v[66:81]
	v_mfma_f32_32x32x16_bf16 v[34:49], v[134:137], v[146:149], v[34:49]
	v_mfma_f32_32x32x16_bf16 v[2:17], v[134:137], v[150:153], v[2:17]
	v_mfma_f32_32x32x16_bf16 v[114:129], v[130:133], v[138:141], v[114:129]
	v_mfma_f32_32x32x16_bf16 v[82:97], v[130:133], v[142:145], v[82:97]
	v_mfma_f32_32x32x16_bf16 v[50:65], v[130:133], v[146:149], v[50:65]
	v_mfma_f32_32x32x16_bf16 v[18:33], v[130:133], v[150:153], v[18:33]
	ds_read_b128 v[130:133], v0
	ds_read_b128 v[134:137], v0 offset:4096
	v_add3_u32 v0, s24, v199, v174
	ds_read_b128 v[138:141], v0
	ds_read_b128 v[142:145], v0 offset:4096
	ds_read_b128 v[146:149], v0 offset:8192
	ds_read_b128 v[150:153], v0 offset:12288
	v_add3_u32 v0, s25, v176, v175
	s_waitcnt lgkmcnt(0)
	v_mfma_f32_32x32x16_bf16 v[98:113], v[134:137], v[138:141], v[98:113]
	v_mfma_f32_32x32x16_bf16 v[66:81], v[134:137], v[142:145], v[66:81]
	v_mfma_f32_32x32x16_bf16 v[34:49], v[134:137], v[146:149], v[34:49]
	v_mfma_f32_32x32x16_bf16 v[2:17], v[134:137], v[150:153], v[2:17]
	v_mfma_f32_32x32x16_bf16 v[114:129], v[130:133], v[138:141], v[114:129]
	v_mfma_f32_32x32x16_bf16 v[82:97], v[130:133], v[142:145], v[82:97]
	v_mfma_f32_32x32x16_bf16 v[50:65], v[130:133], v[146:149], v[50:65]
	v_mfma_f32_32x32x16_bf16 v[18:33], v[130:133], v[150:153], v[18:33]
	ds_read_b128 v[130:133], v0
	ds_read_b128 v[134:137], v0 offset:4096
	v_add3_u32 v0, s24, v176, v174
	ds_read_b128 v[138:141], v0
	ds_read_b128 v[142:145], v0 offset:4096
	ds_read_b128 v[146:149], v0 offset:8192
	ds_read_b128 v[150:153], v0 offset:12288
	v_lshl_add_u32 v0, v165, 7, s16
	s_waitcnt vmcnt(0)
	s_waitcnt vmcnt(0) lgkmcnt(0)
	s_barrier
	v_mfma_f32_32x32x16_bf16 v[98:113], v[134:137], v[138:141], v[98:113]
	s_barrier
	v_mfma_f32_32x32x16_bf16 v[66:81], v[134:137], v[142:145], v[66:81]
	v_mfma_f32_32x32x16_bf16 v[34:49], v[134:137], v[146:149], v[34:49]
	v_mfma_f32_32x32x16_bf16 v[2:17], v[134:137], v[150:153], v[2:17]
	v_lshl_add_u32 v134, v167, 6, s17
	v_ashrrev_i32_e32 v135, 31, v134
	v_mfma_f32_32x32x16_bf16 v[114:129], v[130:133], v[138:141], v[114:129]
	v_mfma_f32_32x32x16_bf16 v[82:97], v[130:133], v[142:145], v[82:97]
	v_mfma_f32_32x32x16_bf16 v[50:65], v[130:133], v[146:149], v[50:65]
	v_mfma_f32_32x32x16_bf16 v[18:33], v[130:133], v[150:153], v[18:33]
	v_or_b32_e32 v130, v0, v166
	v_lshl_add_u64 v[132:133], v[134:135], 1, s[40:41]
	v_lshlrev_b32_e32 v0, 3, v164
	v_and_b32_e32 v131, 64, v183
	v_lshl_add_u64 v[132:133], v[132:133], 0, v[0:1]
	v_xor_b32_e32 v0, 32, v183
	v_add_u32_e32 v131, 64, v131
	v_cmp_lt_i32_e32 vcc, v0, v131
	v_lshrrev_b32_e32 v131, 6, v134
	v_mul_lo_u32 v134, v131, s2
	v_ashrrev_i32_e32 v131, 31, v130
	v_lshlrev_b64 v[136:137], 11, v[130:131]
	v_lshl_add_u64 v[136:137], v[132:133], 0, v[136:137]
	global_load_dwordx2 v[204:205], v[136:137], off
	global_load_dwordx2 v[206:207], v[136:137], off offset:16
	global_load_dwordx2 v[208:209], v[136:137], off offset:32
	global_load_dwordx2 v[210:211], v[136:137], off offset:48
	global_load_dwordx2 v[212:213], v[136:137], off offset:64
	global_load_dwordx2 v[214:215], v[136:137], off offset:80
	global_load_dwordx2 v[216:217], v[136:137], off offset:96
	global_load_dwordx2 v[218:219], v[136:137], off offset:112
	v_cndmask_b32_e32 v0, v183, v0, vcc
	v_lshlrev_b32_e32 v0, 2, v0
	v_ashrrev_i32_e32 v135, 31, v134
	v_lshl_add_u64 v[134:135], s[44:45], 0, v[134:135]
	v_cmp_gt_u32_e32 vcc, 32, v162
	s_waitcnt vmcnt(7)
	v_lshlrev_b32_e32 v140, 16, v204
	v_and_b32_e32 v141, 0xffff0000, v204
	v_lshlrev_b32_e32 v138, 16, v205
	v_and_b32_e32 v139, 0xffff0000, v205
	v_pk_fma_f32 v[114:115], v[114:115], 0.5, v[140:141] op_sel_hi:[1,0,1]
	v_pk_fma_f32 v[116:117], v[116:117], 0.5, v[138:139] op_sel_hi:[1,0,1]
	v_cvt_pk_bf16_f32 v114, v114, v115
	v_cvt_pk_bf16_f32 v115, v116, v117
	global_store_dwordx2 v[136:137], v[114:115], off
	v_lshlrev_b32_e32 v116, 16, v114
	v_and_b32_e32 v114, 0xffff0000, v114
	v_mul_f32_e32 v138, v114, v114
	v_lshlrev_b32_e32 v117, 16, v115
	v_fmac_f32_e32 v138, v116, v116
	v_and_b32_e32 v115, 0xffff0000, v115
	v_fmac_f32_e32 v138, v117, v117
	v_fmac_f32_e32 v138, v115, v115
	s_waitcnt vmcnt(7)
; DI unsigned pack2(float a, float b) { fl2_t f; f.x = a; f.y = b; bf16x2_t r = __builtin_convertvector(f, bf16x2_t); return __builtin_bit_cast(unsigned, r); }
; DI float bflo(unsigned u) { return __uint_as_float(u << 16); }
; DI float bfhi(unsigned u) { return __uint_as_float(u & 0xffff0000u); }
;     ...
;     } else if (EPI == EPI_RES) {
;       float ss = 0.f;
; #pragma unroll
;       for (int j = 0; j < 2; ++j)
; #pragma unroll
;         for (int gq = 0; gq < 4; ++gq) {
;           u16* hp = p.hb + (size_t)m * 1024 + nw + j * 32 + 8 * gq + 4 * hh;
;           uint2 old = *(const uint2*)hp;
;           float h0 = bflo(old.x) + g.scale * acc[i][j][4 * gq + 0];
;           float h1 = bfhi(old.x) + g.scale * acc[i][j][4 * gq + 1];
;           float h2 = bflo(old.y) + g.scale * acc[i][j][4 * gq + 2];
;           float h3 = bfhi(old.y) + g.scale * acc[i][j][4 * gq + 3];
;           unsigned p0 = pack2(h0, h1), p1 = pack2(h2, h3);
;           *(uint2*)hp = make_uint2(p0, p1);
;           float r0 = bflo(p0), r1 = bfhi(p0), r2 = bflo(p1), r3 = bfhi(p1);
;           ss += r0 * r0 + r1 * r1 + r2 * r2 + r3 * r3;
;         }
;       ss += __shfl_xor(ss, 32);
;       if (hh == 0) p.ssq[(size_t)(nw >> 6) * TP + m] = ss;
	v_lshlrev_b32_e32 v116, 16, v206
	v_and_b32_e32 v117, 0xffff0000, v206
	v_pk_fma_f32 v[116:117], v[118:119], 0.5, v[116:117] op_sel_hi:[1,0,1]
	v_lshlrev_b32_e32 v114, 16, v207
	v_and_b32_e32 v115, 0xffff0000, v207
	v_pk_fma_f32 v[114:115], v[120:121], 0.5, v[114:115] op_sel_hi:[1,0,1]
	v_cvt_pk_bf16_f32 v116, v116, v117
	v_cvt_pk_bf16_f32 v117, v114, v115
	v_and_b32_e32 v115, 0xffff0000, v116
	v_lshlrev_b32_e32 v114, 16, v116
	v_mul_f32_e32 v115, v115, v115
	global_store_dwordx2 v[136:137], v[116:117], off offset:16
	v_lshlrev_b32_e32 v116, 16, v117
	v_fmac_f32_e32 v115, v114, v114
	v_and_b32_e32 v117, 0xffff0000, v117
	v_fmac_f32_e32 v115, v116, v116
	v_fmac_f32_e32 v115, v117, v117
	v_add_f32_e32 v118, v138, v115
	s_waitcnt vmcnt(7)
	v_lshlrev_b32_e32 v116, 16, v208
	v_and_b32_e32 v117, 0xffff0000, v208
	v_pk_fma_f32 v[116:117], v[122:123], 0.5, v[116:117] op_sel_hi:[1,0,1]
	v_lshlrev_b32_e32 v114, 16, v209
	v_and_b32_e32 v115, 0xffff0000, v209
	v_pk_fma_f32 v[114:115], v[124:125], 0.5, v[114:115] op_sel_hi:[1,0,1]
	v_cvt_pk_bf16_f32 v116, v116, v117
	v_cvt_pk_bf16_f32 v117, v114, v115
	v_and_b32_e32 v115, 0xffff0000, v116
	v_lshlrev_b32_e32 v114, 16, v116
	v_mul_f32_e32 v115, v115, v115
	global_store_dwordx2 v[136:137], v[116:117], off offset:32
	v_lshlrev_b32_e32 v116, 16, v117
	v_fmac_f32_e32 v115, v114, v114
	v_and_b32_e32 v117, 0xffff0000, v117
	v_fmac_f32_e32 v115, v116, v116
	v_fmac_f32_e32 v115, v117, v117
	v_add_f32_e32 v118, v118, v115
	s_waitcnt vmcnt(7)
	v_lshlrev_b32_e32 v116, 16, v210
	v_and_b32_e32 v117, 0xffff0000, v210
	v_pk_fma_f32 v[116:117], v[126:127], 0.5, v[116:117] op_sel_hi:[1,0,1]
	v_lshlrev_b32_e32 v114, 16, v211
	v_and_b32_e32 v115, 0xffff0000, v211
	v_pk_fma_f32 v[114:115], v[128:129], 0.5, v[114:115] op_sel_hi:[1,0,1]
	v_cvt_pk_bf16_f32 v116, v116, v117
	v_cvt_pk_bf16_f32 v117, v114, v115
	v_and_b32_e32 v115, 0xffff0000, v116
	v_lshlrev_b32_e32 v114, 16, v116
	v_mul_f32_e32 v115, v115, v115
	global_store_dwordx2 v[136:137], v[116:117], off offset:48
	v_lshlrev_b32_e32 v116, 16, v117
	v_fmac_f32_e32 v115, v114, v114
	v_and_b32_e32 v117, 0xffff0000, v117
	v_fmac_f32_e32 v115, v116, v116
	v_fmac_f32_e32 v115, v117, v117
	v_add_f32_e32 v118, v118, v115
	s_waitcnt vmcnt(7)
	v_lshlrev_b32_e32 v116, 16, v212
	v_and_b32_e32 v117, 0xffff0000, v212
	v_lshlrev_b32_e32 v114, 16, v213
	v_and_b32_e32 v115, 0xffff0000, v213
	v_pk_fma_f32 v[98:99], v[98:99], 0.5, v[116:117] op_sel_hi:[1,0,1]
	v_pk_fma_f32 v[100:101], v[100:101], 0.5, v[114:115] op_sel_hi:[1,0,1]
	v_cvt_pk_bf16_f32 v98, v98, v99
	v_cvt_pk_bf16_f32 v99, v100, v101
	global_store_dwordx2 v[136:137], v[98:99], off offset:64
	v_lshlrev_b32_e32 v100, 16, v98
	v_and_b32_e32 v98, 0xffff0000, v98
	v_mul_f32_e32 v98, v98, v98
	v_lshlrev_b32_e32 v101, 16, v99
	v_fmac_f32_e32 v98, v100, v100
	v_and_b32_e32 v99, 0xffff0000, v99
	v_fmac_f32_e32 v98, v101, v101
	v_fmac_f32_e32 v98, v99, v99
	v_add_f32_e32 v114, v118, v98
	s_waitcnt vmcnt(7)
	v_lshlrev_b32_e32 v100, 16, v214
	v_and_b32_e32 v101, 0xffff0000, v214
	v_pk_fma_f32 v[100:101], v[102:103], 0.5, v[100:101] op_sel_hi:[1,0,1]
	v_lshlrev_b32_e32 v98, 16, v215
	v_and_b32_e32 v99, 0xffff0000, v215
	v_pk_fma_f32 v[98:99], v[104:105], 0.5, v[98:99] op_sel_hi:[1,0,1]
	v_cvt_pk_bf16_f32 v100, v100, v101
	v_cvt_pk_bf16_f32 v101, v98, v99
	v_and_b32_e32 v99, 0xffff0000, v100
	v_lshlrev_b32_e32 v98, 16, v100
	v_mul_f32_e32 v99, v99, v99
	global_store_dwordx2 v[136:137], v[100:101], off offset:80
	v_lshlrev_b32_e32 v100, 16, v101
	v_fmac_f32_e32 v99, v98, v98
	v_and_b32_e32 v101, 0xffff0000, v101
	v_fmac_f32_e32 v99, v100, v100
	v_fmac_f32_e32 v99, v101, v101
	v_add_f32_e32 v102, v114, v99
	s_waitcnt vmcnt(7)
	v_lshlrev_b32_e32 v100, 16, v216
	v_and_b32_e32 v101, 0xffff0000, v216
	v_pk_fma_f32 v[100:101], v[106:107], 0.5, v[100:101] op_sel_hi:[1,0,1]
	v_lshlrev_b32_e32 v98, 16, v217
	v_and_b32_e32 v99, 0xffff0000, v217
	v_pk_fma_f32 v[98:99], v[108:109], 0.5, v[98:99] op_sel_hi:[1,0,1]
	v_cvt_pk_bf16_f32 v100, v100, v101
	v_cvt_pk_bf16_f32 v101, v98, v99
	v_and_b32_e32 v99, 0xffff0000, v100
	v_lshlrev_b32_e32 v98, 16, v100
	v_mul_f32_e32 v99, v99, v99
	global_store_dwordx2 v[136:137], v[100:101], off offset:96
	v_lshlrev_b32_e32 v100, 16, v101
	v_fmac_f32_e32 v99, v98, v98
	v_and_b32_e32 v101, 0xffff0000, v101
	v_fmac_f32_e32 v99, v100, v100
	v_fmac_f32_e32 v99, v101, v101
	v_add_f32_e32 v100, v102, v99
	s_waitcnt vmcnt(7)
	v_lshlrev_b32_e32 v102, 16, v218
	v_and_b32_e32 v103, 0xffff0000, v218
	v_pk_fma_f32 v[102:103], v[110:111], 0.5, v[102:103] op_sel_hi:[1,0,1]
	v_lshlrev_b32_e32 v98, 16, v219
	v_and_b32_e32 v99, 0xffff0000, v219
	v_pk_fma_f32 v[98:99], v[112:113], 0.5, v[98:99] op_sel_hi:[1,0,1]
	v_cvt_pk_bf16_f32 v102, v102, v103
	v_cvt_pk_bf16_f32 v103, v98, v99
	v_and_b32_e32 v99, 0xffff0000, v102
	v_lshlrev_b32_e32 v98, 16, v102
	v_mul_f32_e32 v99, v99, v99
	v_lshlrev_b32_e32 v101, 16, v103
	v_fmac_f32_e32 v99, v98, v98
	global_store_dwordx2 v[136:137], v[102:103], off offset:112
	v_and_b32_e32 v102, 0xffff0000, v103
	v_fmac_f32_e32 v99, v101, v101
	v_fmac_f32_e32 v99, v102, v102
	v_add_f32_e32 v100, v100, v99
	ds_bpermute_b32 v101, v0, v100
	v_lshl_add_u64 v[98:99], v[130:131], 2, v[134:135]
	s_and_saveexec_b64 s[2:3], vcc
	s_cbranch_execz .LBB0_1279
	s_waitcnt lgkmcnt(0)
	v_add_f32_e32 v100, v100, v101
	global_store_dword v[98:99], v100, off
; DI unsigned pack2(float a, float b) { fl2_t f; f.x = a; f.y = b; bf16x2_t r = __builtin_convertvector(f, bf16x2_t); return __builtin_bit_cast(unsigned, r); }
; DI float bflo(unsigned u) { return __uint_as_float(u << 16); }
; DI float bfhi(unsigned u) { return __uint_as_float(u & 0xffff0000u); }
;     ...
;     } else if (EPI == EPI_RES) {
;       float ss = 0.f;
; #pragma unroll
;       for (int j = 0; j < 2; ++j)
; #pragma unroll
;         for (int gq = 0; gq < 4; ++gq) {
;           u16* hp = p.hb + (size_t)m * 1024 + nw + j * 32 + 8 * gq + 4 * hh;
;           uint2 old = *(const uint2*)hp;
;           float h0 = bflo(old.x) + g.scale * acc[i][j][4 * gq + 0];
;           float h1 = bfhi(old.x) + g.scale * acc[i][j][4 * gq + 1];
;           float h2 = bflo(old.y) + g.scale * acc[i][j][4 * gq + 2];
;           float h3 = bfhi(old.y) + g.scale * acc[i][j][4 * gq + 3];
;           unsigned p0 = pack2(h0, h1), p1 = pack2(h2, h3);
;           *(uint2*)hp = make_uint2(p0, p1);
;           float r0 = bflo(p0), r1 = bfhi(p0), r2 = bflo(p1), r3 = bfhi(p1);
;           ss += r0 * r0 + r1 * r1 + r2 * r2 + r3 * r3;
;         }
;       ss += __shfl_xor(ss, 32);
;       if (hh == 0) p.ssq[(size_t)(nw >> 6) * TP + m] = ss;
.LBB0_1279:
	s_or_b64 exec, exec, s[2:3]
	v_or_b32_e32 v100, 32, v130
	s_waitcnt lgkmcnt(0)
	v_ashrrev_i32_e32 v101, 31, v100
	v_lshlrev_b64 v[100:101], 11, v[100:101]
	v_lshl_add_u64 v[100:101], v[132:133], 0, v[100:101]
	global_load_dwordx2 v[204:205], v[100:101], off
	global_load_dwordx2 v[206:207], v[100:101], off offset:16
	global_load_dwordx2 v[208:209], v[100:101], off offset:32
	global_load_dwordx2 v[210:211], v[100:101], off offset:48
	global_load_dwordx2 v[212:213], v[100:101], off offset:64
	global_load_dwordx2 v[214:215], v[100:101], off offset:80
	global_load_dwordx2 v[216:217], v[100:101], off offset:96
	global_load_dwordx2 v[218:219], v[100:101], off offset:112
	s_waitcnt vmcnt(7)
	v_lshlrev_b32_e32 v104, 16, v204
	v_and_b32_e32 v105, 0xffff0000, v204
	v_lshlrev_b32_e32 v102, 16, v205
	v_and_b32_e32 v103, 0xffff0000, v205
	v_pk_fma_f32 v[82:83], v[82:83], 0.5, v[104:105] op_sel_hi:[1,0,1]
	v_pk_fma_f32 v[84:85], v[84:85], 0.5, v[102:103] op_sel_hi:[1,0,1]
	v_cvt_pk_bf16_f32 v82, v82, v83
	v_cvt_pk_bf16_f32 v83, v84, v85
	global_store_dwordx2 v[100:101], v[82:83], off
	v_lshlrev_b32_e32 v84, 16, v82
	v_and_b32_e32 v82, 0xffff0000, v82
	v_mul_f32_e32 v102, v82, v82
	v_lshlrev_b32_e32 v85, 16, v83
	v_fmac_f32_e32 v102, v84, v84
	v_and_b32_e32 v83, 0xffff0000, v83
	v_fmac_f32_e32 v102, v85, v85
	v_fmac_f32_e32 v102, v83, v83
	s_waitcnt vmcnt(7)
	v_lshlrev_b32_e32 v84, 16, v206
	v_and_b32_e32 v85, 0xffff0000, v206
	v_pk_fma_f32 v[84:85], v[86:87], 0.5, v[84:85] op_sel_hi:[1,0,1]
	v_lshlrev_b32_e32 v82, 16, v207
	v_and_b32_e32 v83, 0xffff0000, v207
	v_pk_fma_f32 v[82:83], v[88:89], 0.5, v[82:83] op_sel_hi:[1,0,1]
	v_cvt_pk_bf16_f32 v84, v84, v85
	v_cvt_pk_bf16_f32 v85, v82, v83
	v_and_b32_e32 v83, 0xffff0000, v84
	v_lshlrev_b32_e32 v82, 16, v84
	v_mul_f32_e32 v83, v83, v83
	global_store_dwordx2 v[100:101], v[84:85], off offset:16
	v_lshlrev_b32_e32 v84, 16, v85
	v_fmac_f32_e32 v83, v82, v82
	v_and_b32_e32 v85, 0xffff0000, v85
	v_fmac_f32_e32 v83, v84, v84
	v_fmac_f32_e32 v83, v85, v85
	v_add_f32_e32 v86, v102, v83
	s_waitcnt vmcnt(7)
	v_lshlrev_b32_e32 v84, 16, v208
	v_and_b32_e32 v85, 0xffff0000, v208
	v_pk_fma_f32 v[84:85], v[90:91], 0.5, v[84:85] op_sel_hi:[1,0,1]
	v_lshlrev_b32_e32 v82, 16, v209
	v_and_b32_e32 v83, 0xffff0000, v209
	v_pk_fma_f32 v[82:83], v[92:93], 0.5, v[82:83] op_sel_hi:[1,0,1]
	v_cvt_pk_bf16_f32 v84, v84, v85
	v_cvt_pk_bf16_f32 v85, v82, v83
	v_and_b32_e32 v83, 0xffff0000, v84
	v_lshlrev_b32_e32 v82, 16, v84
	v_mul_f32_e32 v83, v83, v83
	global_store_dwordx2 v[100:101], v[84:85], off offset:32
	v_lshlrev_b32_e32 v84, 16, v85
	v_fmac_f32_e32 v83, v82, v82
	v_and_b32_e32 v85, 0xffff0000, v85
	v_fmac_f32_e32 v83, v84, v84
	v_fmac_f32_e32 v83, v85, v85
	v_add_f32_e32 v86, v86, v83
	s_waitcnt vmcnt(7)
	v_lshlrev_b32_e32 v84, 16, v210
	v_and_b32_e32 v85, 0xffff0000, v210
	v_pk_fma_f32 v[84:85], v[94:95], 0.5, v[84:85] op_sel_hi:[1,0,1]
	v_lshlrev_b32_e32 v82, 16, v211
	v_and_b32_e32 v83, 0xffff0000, v211
	v_pk_fma_f32 v[82:83], v[96:97], 0.5, v[82:83] op_sel_hi:[1,0,1]
	v_cvt_pk_bf16_f32 v84, v84, v85
	v_cvt_pk_bf16_f32 v85, v82, v83
	v_and_b32_e32 v83, 0xffff0000, v84
	v_lshlrev_b32_e32 v82, 16, v84
	v_mul_f32_e32 v83, v83, v83
	global_store_dwordx2 v[100:101], v[84:85], off offset:48
	v_lshlrev_b32_e32 v84, 16, v85
	v_fmac_f32_e32 v83, v82, v82
	v_and_b32_e32 v85, 0xffff0000, v85
	v_fmac_f32_e32 v83, v84, v84
	v_fmac_f32_e32 v83, v85, v85
	v_add_f32_e32 v86, v86, v83
	s_waitcnt vmcnt(7)
	v_lshlrev_b32_e32 v84, 16, v212
	v_and_b32_e32 v85, 0xffff0000, v212
	v_lshlrev_b32_e32 v82, 16, v213
	v_and_b32_e32 v83, 0xffff0000, v213
	v_pk_fma_f32 v[66:67], v[66:67], 0.5, v[84:85] op_sel_hi:[1,0,1]
	v_pk_fma_f32 v[68:69], v[68:69], 0.5, v[82:83] op_sel_hi:[1,0,1]
	v_cvt_pk_bf16_f32 v66, v66, v67
	v_cvt_pk_bf16_f32 v67, v68, v69
	global_store_dwordx2 v[100:101], v[66:67], off offset:64
	v_lshlrev_b32_e32 v68, 16, v66
	v_and_b32_e32 v66, 0xffff0000, v66
	v_mul_f32_e32 v66, v66, v66
	v_lshlrev_b32_e32 v69, 16, v67
	v_fmac_f32_e32 v66, v68, v68
	v_and_b32_e32 v67, 0xffff0000, v67
	v_fmac_f32_e32 v66, v69, v69
	v_fmac_f32_e32 v66, v67, v67
	v_add_f32_e32 v82, v86, v66
	s_waitcnt vmcnt(7)
	v_lshlrev_b32_e32 v68, 16, v214
	v_and_b32_e32 v69, 0xffff0000, v214
	v_pk_fma_f32 v[68:69], v[70:71], 0.5, v[68:69] op_sel_hi:[1,0,1]
	v_lshlrev_b32_e32 v66, 16, v215
	v_and_b32_e32 v67, 0xffff0000, v215
	v_pk_fma_f32 v[66:67], v[72:73], 0.5, v[66:67] op_sel_hi:[1,0,1]
	v_cvt_pk_bf16_f32 v68, v68, v69
	v_cvt_pk_bf16_f32 v69, v66, v67
	v_and_b32_e32 v67, 0xffff0000, v68
	v_lshlrev_b32_e32 v66, 16, v68
	v_mul_f32_e32 v67, v67, v67
	global_store_dwordx2 v[100:101], v[68:69], off offset:80
	v_lshlrev_b32_e32 v68, 16, v69
	v_fmac_f32_e32 v67, v66, v66
	v_and_b32_e32 v69, 0xffff0000, v69
	v_fmac_f32_e32 v67, v68, v68
	v_fmac_f32_e32 v67, v69, v69
	v_add_f32_e32 v70, v82, v67
	s_waitcnt vmcnt(7)
	v_lshlrev_b32_e32 v68, 16, v216
	v_and_b32_e32 v69, 0xffff0000, v216
	v_pk_fma_f32 v[68:69], v[74:75], 0.5, v[68:69] op_sel_hi:[1,0,1]
	v_lshlrev_b32_e32 v66, 16, v217
	v_and_b32_e32 v67, 0xffff0000, v217
	v_pk_fma_f32 v[66:67], v[76:77], 0.5, v[66:67] op_sel_hi:[1,0,1]
	v_cvt_pk_bf16_f32 v68, v68, v69
	v_cvt_pk_bf16_f32 v69, v66, v67
	v_and_b32_e32 v67, 0xffff0000, v68
	v_lshlrev_b32_e32 v66, 16, v68
	v_mul_f32_e32 v67, v67, v67
	global_store_dwordx2 v[100:101], v[68:69], off offset:96
	v_lshlrev_b32_e32 v68, 16, v69
	v_fmac_f32_e32 v67, v66, v66
	v_and_b32_e32 v69, 0xffff0000, v69
	v_fmac_f32_e32 v67, v68, v68
	v_fmac_f32_e32 v67, v69, v69
	v_add_f32_e32 v68, v70, v67
	s_waitcnt vmcnt(7)
	v_lshlrev_b32_e32 v70, 16, v218
	v_and_b32_e32 v71, 0xffff0000, v218
	v_pk_fma_f32 v[70:71], v[78:79], 0.5, v[70:71] op_sel_hi:[1,0,1]
	v_lshlrev_b32_e32 v66, 16, v219
	v_and_b32_e32 v67, 0xffff0000, v219
	v_pk_fma_f32 v[66:67], v[80:81], 0.5, v[66:67] op_sel_hi:[1,0,1]
	v_cvt_pk_bf16_f32 v70, v70, v71
	v_cvt_pk_bf16_f32 v71, v66, v67
	v_and_b32_e32 v67, 0xffff0000, v70
	v_lshlrev_b32_e32 v66, 16, v70
	v_mul_f32_e32 v67, v67, v67
	v_lshlrev_b32_e32 v69, 16, v71
	v_fmac_f32_e32 v67, v66, v66
	global_store_dwordx2 v[100:101], v[70:71], off offset:112
	v_and_b32_e32 v70, 0xffff0000, v71
	v_fmac_f32_e32 v67, v69, v69
	v_fmac_f32_e32 v67, v70, v70
	v_add_f32_e32 v66, v68, v67
	ds_bpermute_b32 v67, v0, v66
	s_and_saveexec_b64 s[2:3], vcc
	s_cbranch_execz .LBB0_1281
	s_waitcnt lgkmcnt(0)
	v_add_f32_e32 v66, v66, v67
	global_store_dword v[98:99], v66, off offset:128
; DI unsigned pack2(float a, float b) { fl2_t f; f.x = a; f.y = b; bf16x2_t r = __builtin_convertvector(f, bf16x2_t); return __builtin_bit_cast(unsigned, r); }
; DI float bflo(unsigned u) { return __uint_as_float(u << 16); }
; DI float bfhi(unsigned u) { return __uint_as_float(u & 0xffff0000u); }
;     ...
;     } else if (EPI == EPI_RES) {
;       float ss = 0.f;
; #pragma unroll
;       for (int j = 0; j < 2; ++j)
; #pragma unroll
;         for (int gq = 0; gq < 4; ++gq) {
;           u16* hp = p.hb + (size_t)m * 1024 + nw + j * 32 + 8 * gq + 4 * hh;
;           uint2 old = *(const uint2*)hp;
;           float h0 = bflo(old.x) + g.scale * acc[i][j][4 * gq + 0];
;           float h1 = bfhi(old.x) + g.scale * acc[i][j][4 * gq + 1];
;           float h2 = bflo(old.y) + g.scale * acc[i][j][4 * gq + 2];
;           float h3 = bfhi(old.y) + g.scale * acc[i][j][4 * gq + 3];
;           unsigned p0 = pack2(h0, h1), p1 = pack2(h2, h3);
;           *(uint2*)hp = make_uint2(p0, p1);
;           float r0 = bflo(p0), r1 = bfhi(p0), r2 = bflo(p1), r3 = bfhi(p1);
;           ss += r0 * r0 + r1 * r1 + r2 * r2 + r3 * r3;
;         }
;       ss += __shfl_xor(ss, 32);
;       if (hh == 0) p.ssq[(size_t)(nw >> 6) * TP + m] = ss;
.LBB0_1281:
	s_or_b64 exec, exec, s[2:3]
	v_or_b32_e32 v66, 64, v130
	s_waitcnt lgkmcnt(0)
	v_ashrrev_i32_e32 v67, 31, v66
	v_lshlrev_b64 v[66:67], 11, v[66:67]
	v_lshl_add_u64 v[66:67], v[132:133], 0, v[66:67]
	global_load_dwordx2 v[204:205], v[66:67], off
	global_load_dwordx2 v[206:207], v[66:67], off offset:16
	global_load_dwordx2 v[208:209], v[66:67], off offset:32
	global_load_dwordx2 v[210:211], v[66:67], off offset:48
	global_load_dwordx2 v[212:213], v[66:67], off offset:64
	global_load_dwordx2 v[214:215], v[66:67], off offset:80
	global_load_dwordx2 v[216:217], v[66:67], off offset:96
	global_load_dwordx2 v[218:219], v[66:67], off offset:112
	s_waitcnt vmcnt(7)
	v_lshlrev_b32_e32 v70, 16, v204
	v_and_b32_e32 v71, 0xffff0000, v204
	v_lshlrev_b32_e32 v68, 16, v205
	v_and_b32_e32 v69, 0xffff0000, v205
	v_pk_fma_f32 v[50:51], v[50:51], 0.5, v[70:71] op_sel_hi:[1,0,1]
	v_pk_fma_f32 v[52:53], v[52:53], 0.5, v[68:69] op_sel_hi:[1,0,1]
	v_cvt_pk_bf16_f32 v50, v50, v51
	v_cvt_pk_bf16_f32 v51, v52, v53
	global_store_dwordx2 v[66:67], v[50:51], off
	v_lshlrev_b32_e32 v52, 16, v50
	v_and_b32_e32 v50, 0xffff0000, v50
	v_mul_f32_e32 v68, v50, v50
	v_lshlrev_b32_e32 v53, 16, v51
	v_fmac_f32_e32 v68, v52, v52
	v_and_b32_e32 v51, 0xffff0000, v51
	v_fmac_f32_e32 v68, v53, v53
	v_fmac_f32_e32 v68, v51, v51
	s_waitcnt vmcnt(7)
	v_lshlrev_b32_e32 v52, 16, v206
	v_and_b32_e32 v53, 0xffff0000, v206
	v_pk_fma_f32 v[52:53], v[54:55], 0.5, v[52:53] op_sel_hi:[1,0,1]
	v_lshlrev_b32_e32 v50, 16, v207
	v_and_b32_e32 v51, 0xffff0000, v207
	v_pk_fma_f32 v[50:51], v[56:57], 0.5, v[50:51] op_sel_hi:[1,0,1]
	v_cvt_pk_bf16_f32 v52, v52, v53
	v_cvt_pk_bf16_f32 v53, v50, v51
	v_and_b32_e32 v51, 0xffff0000, v52
	v_lshlrev_b32_e32 v50, 16, v52
	v_mul_f32_e32 v51, v51, v51
	global_store_dwordx2 v[66:67], v[52:53], off offset:16
	v_lshlrev_b32_e32 v52, 16, v53
	v_fmac_f32_e32 v51, v50, v50
	v_and_b32_e32 v53, 0xffff0000, v53
	v_fmac_f32_e32 v51, v52, v52
	v_fmac_f32_e32 v51, v53, v53
	v_add_f32_e32 v54, v68, v51
	s_waitcnt vmcnt(7)
	v_lshlrev_b32_e32 v52, 16, v208
	v_and_b32_e32 v53, 0xffff0000, v208
	v_pk_fma_f32 v[52:53], v[58:59], 0.5, v[52:53] op_sel_hi:[1,0,1]
	v_lshlrev_b32_e32 v50, 16, v209
	v_and_b32_e32 v51, 0xffff0000, v209
	v_pk_fma_f32 v[50:51], v[60:61], 0.5, v[50:51] op_sel_hi:[1,0,1]
	v_cvt_pk_bf16_f32 v52, v52, v53
	v_cvt_pk_bf16_f32 v53, v50, v51
	v_and_b32_e32 v51, 0xffff0000, v52
	v_lshlrev_b32_e32 v50, 16, v52
	v_mul_f32_e32 v51, v51, v51
	global_store_dwordx2 v[66:67], v[52:53], off offset:32
	v_lshlrev_b32_e32 v52, 16, v53
	v_fmac_f32_e32 v51, v50, v50
	v_and_b32_e32 v53, 0xffff0000, v53
	v_fmac_f32_e32 v51, v52, v52
	v_fmac_f32_e32 v51, v53, v53
	v_add_f32_e32 v54, v54, v51
	s_waitcnt vmcnt(7)
	v_lshlrev_b32_e32 v52, 16, v210
	v_and_b32_e32 v53, 0xffff0000, v210
	v_pk_fma_f32 v[52:53], v[62:63], 0.5, v[52:53] op_sel_hi:[1,0,1]
	v_lshlrev_b32_e32 v50, 16, v211
	v_and_b32_e32 v51, 0xffff0000, v211
	v_pk_fma_f32 v[50:51], v[64:65], 0.5, v[50:51] op_sel_hi:[1,0,1]
	v_cvt_pk_bf16_f32 v52, v52, v53
	v_cvt_pk_bf16_f32 v53, v50, v51
	v_and_b32_e32 v51, 0xffff0000, v52
	v_lshlrev_b32_e32 v50, 16, v52
	v_mul_f32_e32 v51, v51, v51
	global_store_dwordx2 v[66:67], v[52:53], off offset:48
	v_lshlrev_b32_e32 v52, 16, v53
	v_fmac_f32_e32 v51, v50, v50
	v_and_b32_e32 v53, 0xffff0000, v53
	v_fmac_f32_e32 v51, v52, v52
	v_fmac_f32_e32 v51, v53, v53
	v_add_f32_e32 v54, v54, v51
	s_waitcnt vmcnt(7)
	v_lshlrev_b32_e32 v52, 16, v212
	v_and_b32_e32 v53, 0xffff0000, v212
	v_lshlrev_b32_e32 v50, 16, v213
	v_and_b32_e32 v51, 0xffff0000, v213
	v_pk_fma_f32 v[34:35], v[34:35], 0.5, v[52:53] op_sel_hi:[1,0,1]
	v_pk_fma_f32 v[36:37], v[36:37], 0.5, v[50:51] op_sel_hi:[1,0,1]
	v_cvt_pk_bf16_f32 v34, v34, v35
	v_cvt_pk_bf16_f32 v35, v36, v37
	global_store_dwordx2 v[66:67], v[34:35], off offset:64
	v_lshlrev_b32_e32 v36, 16, v34
	v_and_b32_e32 v34, 0xffff0000, v34
	v_mul_f32_e32 v34, v34, v34
	v_lshlrev_b32_e32 v37, 16, v35
	v_fmac_f32_e32 v34, v36, v36
	v_and_b32_e32 v35, 0xffff0000, v35
	v_fmac_f32_e32 v34, v37, v37
	v_fmac_f32_e32 v34, v35, v35
	v_add_f32_e32 v50, v54, v34
	s_waitcnt vmcnt(7)
	v_lshlrev_b32_e32 v36, 16, v214
	v_and_b32_e32 v37, 0xffff0000, v214
	v_pk_fma_f32 v[36:37], v[38:39], 0.5, v[36:37] op_sel_hi:[1,0,1]
	v_lshlrev_b32_e32 v34, 16, v215
	v_and_b32_e32 v35, 0xffff0000, v215
	v_pk_fma_f32 v[34:35], v[40:41], 0.5, v[34:35] op_sel_hi:[1,0,1]
	v_cvt_pk_bf16_f32 v36, v36, v37
	v_cvt_pk_bf16_f32 v37, v34, v35
	v_and_b32_e32 v35, 0xffff0000, v36
	v_lshlrev_b32_e32 v34, 16, v36
	v_mul_f32_e32 v35, v35, v35
	global_store_dwordx2 v[66:67], v[36:37], off offset:80
	v_lshlrev_b32_e32 v36, 16, v37
	v_fmac_f32_e32 v35, v34, v34
	v_and_b32_e32 v37, 0xffff0000, v37
	v_fmac_f32_e32 v35, v36, v36
	v_fmac_f32_e32 v35, v37, v37
	v_add_f32_e32 v38, v50, v35
	s_waitcnt vmcnt(7)
	v_lshlrev_b32_e32 v36, 16, v216
	v_and_b32_e32 v37, 0xffff0000, v216
	v_pk_fma_f32 v[36:37], v[42:43], 0.5, v[36:37] op_sel_hi:[1,0,1]
	v_lshlrev_b32_e32 v34, 16, v217
	v_and_b32_e32 v35, 0xffff0000, v217
	v_pk_fma_f32 v[34:35], v[44:45], 0.5, v[34:35] op_sel_hi:[1,0,1]
	v_cvt_pk_bf16_f32 v36, v36, v37
	v_cvt_pk_bf16_f32 v37, v34, v35
	v_and_b32_e32 v35, 0xffff0000, v36
	v_lshlrev_b32_e32 v34, 16, v36
	v_mul_f32_e32 v35, v35, v35
	global_store_dwordx2 v[66:67], v[36:37], off offset:96
	v_lshlrev_b32_e32 v36, 16, v37
	v_fmac_f32_e32 v35, v34, v34
	v_and_b32_e32 v37, 0xffff0000, v37
	v_fmac_f32_e32 v35, v36, v36
	v_fmac_f32_e32 v35, v37, v37
	v_add_f32_e32 v36, v38, v35
	s_waitcnt vmcnt(7)
	v_lshlrev_b32_e32 v38, 16, v218
	v_and_b32_e32 v39, 0xffff0000, v218
	v_pk_fma_f32 v[38:39], v[46:47], 0.5, v[38:39] op_sel_hi:[1,0,1]
	v_lshlrev_b32_e32 v34, 16, v219
	v_and_b32_e32 v35, 0xffff0000, v219
	v_pk_fma_f32 v[34:35], v[48:49], 0.5, v[34:35] op_sel_hi:[1,0,1]
	v_cvt_pk_bf16_f32 v38, v38, v39
	v_cvt_pk_bf16_f32 v39, v34, v35
	v_and_b32_e32 v35, 0xffff0000, v38
	v_lshlrev_b32_e32 v34, 16, v38
	v_mul_f32_e32 v35, v35, v35
	v_lshlrev_b32_e32 v37, 16, v39
	v_fmac_f32_e32 v35, v34, v34
	global_store_dwordx2 v[66:67], v[38:39], off offset:112
	v_and_b32_e32 v38, 0xffff0000, v39
	v_fmac_f32_e32 v35, v37, v37
	v_fmac_f32_e32 v35, v38, v38
	v_add_f32_e32 v34, v36, v35
	ds_bpermute_b32 v35, v0, v34
	s_and_saveexec_b64 s[2:3], vcc
	s_cbranch_execz .LBB0_1283
	s_waitcnt lgkmcnt(0)
	v_add_f32_e32 v34, v34, v35
	global_store_dword v[98:99], v34, off offset:256
; DI unsigned pack2(float a, float b) { fl2_t f; f.x = a; f.y = b; bf16x2_t r = __builtin_convertvector(f, bf16x2_t); return __builtin_bit_cast(unsigned, r); }
; DI float bflo(unsigned u) { return __uint_as_float(u << 16); }
; DI float bfhi(unsigned u) { return __uint_as_float(u & 0xffff0000u); }
;     ...
;     } else if (EPI == EPI_RES) {
;       float ss = 0.f;
; #pragma unroll
;       for (int j = 0; j < 2; ++j)
; #pragma unroll
;         for (int gq = 0; gq < 4; ++gq) {
;           u16* hp = p.hb + (size_t)m * 1024 + nw + j * 32 + 8 * gq + 4 * hh;
;           uint2 old = *(const uint2*)hp;
;           float h0 = bflo(old.x) + g.scale * acc[i][j][4 * gq + 0];
;           float h1 = bfhi(old.x) + g.scale * acc[i][j][4 * gq + 1];
;           float h2 = bflo(old.y) + g.scale * acc[i][j][4 * gq + 2];
;           float h3 = bfhi(old.y) + g.scale * acc[i][j][4 * gq + 3];
;           unsigned p0 = pack2(h0, h1), p1 = pack2(h2, h3);
;           *(uint2*)hp = make_uint2(p0, p1);
;           float r0 = bflo(p0), r1 = bfhi(p0), r2 = bflo(p1), r3 = bfhi(p1);
;           ss += r0 * r0 + r1 * r1 + r2 * r2 + r3 * r3;
;         }
;       ss += __shfl_xor(ss, 32);
;       if (hh == 0) p.ssq[(size_t)(nw >> 6) * TP + m] = ss;
.LBB0_1283:
	s_or_b64 exec, exec, s[2:3]
	v_or_b32_e32 v34, 0x60, v130
	s_waitcnt lgkmcnt(0)
	v_ashrrev_i32_e32 v35, 31, v34
	v_lshlrev_b64 v[34:35], 11, v[34:35]
	v_lshl_add_u64 v[34:35], v[132:133], 0, v[34:35]
	global_load_dwordx2 v[204:205], v[34:35], off
	global_load_dwordx2 v[206:207], v[34:35], off offset:16
	global_load_dwordx2 v[208:209], v[34:35], off offset:32
	global_load_dwordx2 v[210:211], v[34:35], off offset:48
	global_load_dwordx2 v[212:213], v[34:35], off offset:64
	global_load_dwordx2 v[214:215], v[34:35], off offset:80
	global_load_dwordx2 v[216:217], v[34:35], off offset:96
	global_load_dwordx2 v[218:219], v[34:35], off offset:112
	s_waitcnt vmcnt(7)
	v_lshlrev_b32_e32 v38, 16, v204
	v_and_b32_e32 v39, 0xffff0000, v204
	v_lshlrev_b32_e32 v36, 16, v205
	v_and_b32_e32 v37, 0xffff0000, v205
	v_pk_fma_f32 v[18:19], v[18:19], 0.5, v[38:39] op_sel_hi:[1,0,1]
	v_pk_fma_f32 v[20:21], v[20:21], 0.5, v[36:37] op_sel_hi:[1,0,1]
	v_cvt_pk_bf16_f32 v18, v18, v19
	v_cvt_pk_bf16_f32 v19, v20, v21
	global_store_dwordx2 v[34:35], v[18:19], off
	v_lshlrev_b32_e32 v20, 16, v18
	v_and_b32_e32 v18, 0xffff0000, v18
	v_mul_f32_e32 v36, v18, v18
	v_lshlrev_b32_e32 v21, 16, v19
	v_fmac_f32_e32 v36, v20, v20
	v_and_b32_e32 v19, 0xffff0000, v19
	v_fmac_f32_e32 v36, v21, v21
	v_fmac_f32_e32 v36, v19, v19
	s_waitcnt vmcnt(7)
	v_lshlrev_b32_e32 v20, 16, v206
	v_and_b32_e32 v21, 0xffff0000, v206
	v_pk_fma_f32 v[20:21], v[22:23], 0.5, v[20:21] op_sel_hi:[1,0,1]
	v_lshlrev_b32_e32 v18, 16, v207
	v_and_b32_e32 v19, 0xffff0000, v207
	v_pk_fma_f32 v[18:19], v[24:25], 0.5, v[18:19] op_sel_hi:[1,0,1]
	v_cvt_pk_bf16_f32 v20, v20, v21
	v_cvt_pk_bf16_f32 v21, v18, v19
	v_and_b32_e32 v19, 0xffff0000, v20
	v_lshlrev_b32_e32 v18, 16, v20
	v_mul_f32_e32 v19, v19, v19
	global_store_dwordx2 v[34:35], v[20:21], off offset:16
	v_lshlrev_b32_e32 v20, 16, v21
	v_fmac_f32_e32 v19, v18, v18
	v_and_b32_e32 v21, 0xffff0000, v21
	v_fmac_f32_e32 v19, v20, v20
	v_fmac_f32_e32 v19, v21, v21
	v_add_f32_e32 v22, v36, v19
	s_waitcnt vmcnt(7)
	v_lshlrev_b32_e32 v20, 16, v208
	v_and_b32_e32 v21, 0xffff0000, v208
	v_pk_fma_f32 v[20:21], v[26:27], 0.5, v[20:21] op_sel_hi:[1,0,1]
	v_lshlrev_b32_e32 v18, 16, v209
	v_and_b32_e32 v19, 0xffff0000, v209
	v_pk_fma_f32 v[18:19], v[28:29], 0.5, v[18:19] op_sel_hi:[1,0,1]
	v_cvt_pk_bf16_f32 v20, v20, v21
	v_cvt_pk_bf16_f32 v21, v18, v19
	v_and_b32_e32 v19, 0xffff0000, v20
	v_lshlrev_b32_e32 v18, 16, v20
	v_mul_f32_e32 v19, v19, v19
	global_store_dwordx2 v[34:35], v[20:21], off offset:32
	v_lshlrev_b32_e32 v20, 16, v21
	v_fmac_f32_e32 v19, v18, v18
	v_and_b32_e32 v21, 0xffff0000, v21
	v_fmac_f32_e32 v19, v20, v20
	v_fmac_f32_e32 v19, v21, v21
	v_add_f32_e32 v22, v22, v19
	s_waitcnt vmcnt(7)
	v_lshlrev_b32_e32 v20, 16, v210
	v_and_b32_e32 v21, 0xffff0000, v210
	v_pk_fma_f32 v[20:21], v[30:31], 0.5, v[20:21] op_sel_hi:[1,0,1]
	v_lshlrev_b32_e32 v18, 16, v211
	v_and_b32_e32 v19, 0xffff0000, v211
	v_pk_fma_f32 v[18:19], v[32:33], 0.5, v[18:19] op_sel_hi:[1,0,1]
	v_cvt_pk_bf16_f32 v20, v20, v21
	v_cvt_pk_bf16_f32 v21, v18, v19
	v_and_b32_e32 v19, 0xffff0000, v20
	v_lshlrev_b32_e32 v18, 16, v20
	v_mul_f32_e32 v19, v19, v19
	global_store_dwordx2 v[34:35], v[20:21], off offset:48
	v_lshlrev_b32_e32 v20, 16, v21
	v_fmac_f32_e32 v19, v18, v18
	v_and_b32_e32 v21, 0xffff0000, v21
	v_fmac_f32_e32 v19, v20, v20
	v_fmac_f32_e32 v19, v21, v21
	v_add_f32_e32 v22, v22, v19
	s_waitcnt vmcnt(7)
	v_lshlrev_b32_e32 v20, 16, v212
	v_and_b32_e32 v21, 0xffff0000, v212
	v_lshlrev_b32_e32 v18, 16, v213
	v_and_b32_e32 v19, 0xffff0000, v213
	v_pk_fma_f32 v[2:3], v[2:3], 0.5, v[20:21] op_sel_hi:[1,0,1]
	v_pk_fma_f32 v[4:5], v[4:5], 0.5, v[18:19] op_sel_hi:[1,0,1]
	v_cvt_pk_bf16_f32 v2, v2, v3
	v_cvt_pk_bf16_f32 v3, v4, v5
	global_store_dwordx2 v[34:35], v[2:3], off offset:64
	v_lshlrev_b32_e32 v4, 16, v2
	v_and_b32_e32 v2, 0xffff0000, v2
	v_mul_f32_e32 v2, v2, v2
	v_lshlrev_b32_e32 v5, 16, v3
	v_fmac_f32_e32 v2, v4, v4
	v_and_b32_e32 v3, 0xffff0000, v3
	v_fmac_f32_e32 v2, v5, v5
	v_fmac_f32_e32 v2, v3, v3
	v_add_f32_e32 v18, v22, v2
	s_waitcnt vmcnt(7)
	v_lshlrev_b32_e32 v4, 16, v214
	v_and_b32_e32 v5, 0xffff0000, v214
	v_pk_fma_f32 v[4:5], v[6:7], 0.5, v[4:5] op_sel_hi:[1,0,1]
	v_lshlrev_b32_e32 v2, 16, v215
	v_and_b32_e32 v3, 0xffff0000, v215
	v_pk_fma_f32 v[2:3], v[8:9], 0.5, v[2:3] op_sel_hi:[1,0,1]
	v_cvt_pk_bf16_f32 v4, v4, v5
	v_cvt_pk_bf16_f32 v5, v2, v3
	v_and_b32_e32 v3, 0xffff0000, v4
	v_lshlrev_b32_e32 v2, 16, v4
	v_mul_f32_e32 v3, v3, v3
	global_store_dwordx2 v[34:35], v[4:5], off offset:80
	v_lshlrev_b32_e32 v4, 16, v5
	v_fmac_f32_e32 v3, v2, v2
	v_and_b32_e32 v5, 0xffff0000, v5
	v_fmac_f32_e32 v3, v4, v4
	v_fmac_f32_e32 v3, v5, v5
	v_add_f32_e32 v6, v18, v3
	s_waitcnt vmcnt(7)
	v_lshlrev_b32_e32 v4, 16, v216
	v_and_b32_e32 v5, 0xffff0000, v216
	v_pk_fma_f32 v[4:5], v[10:11], 0.5, v[4:5] op_sel_hi:[1,0,1]
	v_lshlrev_b32_e32 v2, 16, v217
	v_and_b32_e32 v3, 0xffff0000, v217
	v_pk_fma_f32 v[2:3], v[12:13], 0.5, v[2:3] op_sel_hi:[1,0,1]
	v_cvt_pk_bf16_f32 v4, v4, v5
	v_cvt_pk_bf16_f32 v5, v2, v3
	v_and_b32_e32 v3, 0xffff0000, v4
	v_lshlrev_b32_e32 v2, 16, v4
	v_mul_f32_e32 v3, v3, v3
	global_store_dwordx2 v[34:35], v[4:5], off offset:96
	v_lshlrev_b32_e32 v4, 16, v5
	v_fmac_f32_e32 v3, v2, v2
	v_and_b32_e32 v5, 0xffff0000, v5
	v_fmac_f32_e32 v3, v4, v4
	v_fmac_f32_e32 v3, v5, v5
	v_add_f32_e32 v4, v6, v3
	s_waitcnt vmcnt(7)
	v_lshlrev_b32_e32 v6, 16, v218
	v_and_b32_e32 v7, 0xffff0000, v218
	v_pk_fma_f32 v[6:7], v[14:15], 0.5, v[6:7] op_sel_hi:[1,0,1]
	v_lshlrev_b32_e32 v2, 16, v219
	v_and_b32_e32 v3, 0xffff0000, v219
	v_pk_fma_f32 v[2:3], v[16:17], 0.5, v[2:3] op_sel_hi:[1,0,1]
	v_cvt_pk_bf16_f32 v6, v6, v7
	v_cvt_pk_bf16_f32 v7, v2, v3
	v_and_b32_e32 v3, 0xffff0000, v6
	v_lshlrev_b32_e32 v2, 16, v6
	v_mul_f32_e32 v3, v3, v3
	v_lshlrev_b32_e32 v5, 16, v7
	v_fmac_f32_e32 v3, v2, v2
	global_store_dwordx2 v[34:35], v[6:7], off offset:112
	v_and_b32_e32 v6, 0xffff0000, v7
	v_fmac_f32_e32 v3, v5, v5
	v_fmac_f32_e32 v3, v6, v6
	v_add_f32_e32 v2, v4, v3
	ds_bpermute_b32 v0, v0, v2
	s_and_saveexec_b64 s[2:3], vcc
	s_cbranch_execz .LBB0_1268
	s_waitcnt lgkmcnt(0)
	v_add_f32_e32 v0, v2, v0
	global_store_dword v[98:99], v0, off offset:384
	s_branch .LBB0_1268

; DI unsigned pack2(float a, float b) { fl2_t f; f.x = a; f.y = b; bf16x2_t r = __builtin_convertvector(f, bf16x2_t); return __builtin_bit_cast(unsigned, r); }
; DI float bflo(unsigned u) { return __uint_as_float(u << 16); }
; DI float bfhi(unsigned u) { return __uint_as_float(u & 0xffff0000u); }
;     ...
;     } else if (EPI == EPI_RES) {
;       float ss = 0.f;
; #pragma unroll
;       for (int j = 0; j < 2; ++j)
; #pragma unroll
;         for (int gq = 0; gq < 4; ++gq) {
;           u16* hp = p.hb + (size_t)m * 1024 + nw + j * 32 + 8 * gq + 4 * hh;
;           uint2 old = *(const uint2*)hp;
;           float h0 = bflo(old.x) + g.scale * acc[i][j][4 * gq + 0];
;           float h1 = bfhi(old.x) + g.scale * acc[i][j][4 * gq + 1];
;           float h2 = bflo(old.y) + g.scale * acc[i][j][4 * gq + 2];
;           float h3 = bfhi(old.y) + g.scale * acc[i][j][4 * gq + 3];
;           unsigned p0 = pack2(h0, h1), p1 = pack2(h2, h3);
;           *(uint2*)hp = make_uint2(p0, p1);
;           float r0 = bflo(p0), r1 = bfhi(p0), r2 = bflo(p1), r3 = bfhi(p1);
;           ss += r0 * r0 + r1 * r1 + r2 * r2 + r3 * r3;
;         }
;       ss += __shfl_xor(ss, 32);
;       if (hh == 0) p.ssq[(size_t)(nw >> 6) * TP + m] = ss;
.LBB0_1298:
	v_or_b32_e32 v34, v61, v60
	v_ashrrev_i32_e32 v35, 31, v34
	v_lshlrev_b64 v[36:37], 11, v[34:35]
	v_lshl_add_u64 v[36:37], s[40:41], 0, v[36:37]
	s_ashr_i32 s15, s14, 31
	v_lshl_add_u64 v[36:37], s[14:15], 1, v[36:37]
	v_lshlrev_b32_e32 v0, 3, v59
	v_and_b32_e32 v38, 64, v183
	v_lshl_add_u64 v[36:37], v[36:37], 0, v[0:1]
	v_xor_b32_e32 v0, 32, v183
	v_add_u32_e32 v38, 64, v38
	s_waitcnt vmcnt(0)
	s_barrier
	v_cmp_lt_i32_e32 vcc, v0, v38
	global_load_dwordx2 v[130:131], v[36:37], off
	global_load_dwordx2 v[132:133], v[36:37], off offset:16
	global_load_dwordx2 v[134:135], v[36:37], off offset:32
	global_load_dwordx2 v[136:137], v[36:37], off offset:48
	global_load_dwordx2 v[138:139], v[36:37], off offset:64
	global_load_dwordx2 v[140:141], v[36:37], off offset:80
	global_load_dwordx2 v[142:143], v[36:37], off offset:96
	global_load_dwordx2 v[144:145], v[36:37], off offset:112
	s_waitcnt vmcnt(7)
	v_lshlrev_b32_e32 v40, 16, v130
	v_and_b32_e32 v41, 0xffff0000, v130
	v_lshlrev_b32_e32 v38, 16, v131
	v_and_b32_e32 v39, 0xffff0000, v131
	v_pk_fma_f32 v[18:19], v[18:19], 0.5, v[40:41] op_sel_hi:[1,0,1]
	v_pk_fma_f32 v[20:21], v[20:21], 0.5, v[38:39] op_sel_hi:[1,0,1]
	v_cvt_pk_bf16_f32 v18, v18, v19
	v_cvt_pk_bf16_f32 v19, v20, v21
	global_store_dwordx2 v[36:37], v[18:19], off
	v_lshlrev_b32_e32 v20, 16, v18
	v_and_b32_e32 v18, 0xffff0000, v18
	v_mul_f32_e32 v38, v18, v18
	v_lshlrev_b32_e32 v21, 16, v19
	v_fmac_f32_e32 v38, v20, v20
	v_and_b32_e32 v19, 0xffff0000, v19
	v_fmac_f32_e32 v38, v21, v21
	v_fmac_f32_e32 v38, v19, v19
	v_cndmask_b32_e32 v0, v183, v0, vcc
	v_lshlrev_b32_e32 v0, 2, v0
	v_cmp_gt_u32_e32 vcc, 32, v58
	s_waitcnt vmcnt(7)
	v_lshlrev_b32_e32 v20, 16, v132
	v_and_b32_e32 v21, 0xffff0000, v132
	v_pk_fma_f32 v[20:21], v[22:23], 0.5, v[20:21] op_sel_hi:[1,0,1]
	v_lshlrev_b32_e32 v18, 16, v133
	v_and_b32_e32 v19, 0xffff0000, v133
	v_pk_fma_f32 v[18:19], v[24:25], 0.5, v[18:19] op_sel_hi:[1,0,1]
	v_cvt_pk_bf16_f32 v20, v20, v21
	v_cvt_pk_bf16_f32 v21, v18, v19
	v_and_b32_e32 v19, 0xffff0000, v20
	v_lshlrev_b32_e32 v18, 16, v20
	v_mul_f32_e32 v19, v19, v19
	global_store_dwordx2 v[36:37], v[20:21], off offset:16
	v_lshlrev_b32_e32 v20, 16, v21
	v_fmac_f32_e32 v19, v18, v18
	v_and_b32_e32 v21, 0xffff0000, v21
	v_fmac_f32_e32 v19, v20, v20
	v_fmac_f32_e32 v19, v21, v21
	v_add_f32_e32 v22, v38, v19
	s_waitcnt vmcnt(7)
	v_lshlrev_b32_e32 v20, 16, v134
	v_and_b32_e32 v21, 0xffff0000, v134
	v_pk_fma_f32 v[20:21], v[26:27], 0.5, v[20:21] op_sel_hi:[1,0,1]
	v_lshlrev_b32_e32 v18, 16, v135
	v_and_b32_e32 v19, 0xffff0000, v135
	v_pk_fma_f32 v[18:19], v[28:29], 0.5, v[18:19] op_sel_hi:[1,0,1]
	v_cvt_pk_bf16_f32 v20, v20, v21
	v_cvt_pk_bf16_f32 v21, v18, v19
	v_and_b32_e32 v19, 0xffff0000, v20
	v_lshlrev_b32_e32 v18, 16, v20
	v_mul_f32_e32 v19, v19, v19
	global_store_dwordx2 v[36:37], v[20:21], off offset:32
	v_lshlrev_b32_e32 v20, 16, v21
	v_fmac_f32_e32 v19, v18, v18
	v_and_b32_e32 v21, 0xffff0000, v21
	v_fmac_f32_e32 v19, v20, v20
	v_fmac_f32_e32 v19, v21, v21
	v_add_f32_e32 v22, v22, v19
	s_waitcnt vmcnt(7)
	v_lshlrev_b32_e32 v20, 16, v136
	v_and_b32_e32 v21, 0xffff0000, v136
	v_pk_fma_f32 v[20:21], v[30:31], 0.5, v[20:21] op_sel_hi:[1,0,1]
	v_lshlrev_b32_e32 v18, 16, v137
	v_and_b32_e32 v19, 0xffff0000, v137
	v_pk_fma_f32 v[18:19], v[32:33], 0.5, v[18:19] op_sel_hi:[1,0,1]
	v_cvt_pk_bf16_f32 v20, v20, v21
	v_cvt_pk_bf16_f32 v21, v18, v19
	v_and_b32_e32 v19, 0xffff0000, v20
	v_lshlrev_b32_e32 v18, 16, v20
	v_mul_f32_e32 v19, v19, v19
	global_store_dwordx2 v[36:37], v[20:21], off offset:48
	v_lshlrev_b32_e32 v20, 16, v21
	v_fmac_f32_e32 v19, v18, v18
	v_and_b32_e32 v21, 0xffff0000, v21
	v_fmac_f32_e32 v19, v20, v20
	v_fmac_f32_e32 v19, v21, v21
	v_add_f32_e32 v22, v22, v19
	s_waitcnt vmcnt(7)
	v_lshlrev_b32_e32 v20, 16, v138
	v_and_b32_e32 v21, 0xffff0000, v138
	v_lshlrev_b32_e32 v18, 16, v139
	v_and_b32_e32 v19, 0xffff0000, v139
	v_pk_fma_f32 v[2:3], v[2:3], 0.5, v[20:21] op_sel_hi:[1,0,1]
	v_pk_fma_f32 v[4:5], v[4:5], 0.5, v[18:19] op_sel_hi:[1,0,1]
	v_cvt_pk_bf16_f32 v2, v2, v3
	v_cvt_pk_bf16_f32 v3, v4, v5
	global_store_dwordx2 v[36:37], v[2:3], off offset:64
	v_lshlrev_b32_e32 v4, 16, v2
	v_and_b32_e32 v2, 0xffff0000, v2
	v_mul_f32_e32 v2, v2, v2
	v_lshlrev_b32_e32 v5, 16, v3
	v_fmac_f32_e32 v2, v4, v4
	v_and_b32_e32 v3, 0xffff0000, v3
	v_fmac_f32_e32 v2, v5, v5
	v_fmac_f32_e32 v2, v3, v3
	v_add_f32_e32 v18, v22, v2
	s_waitcnt vmcnt(7)
	v_lshlrev_b32_e32 v4, 16, v140
	v_and_b32_e32 v5, 0xffff0000, v140
	v_pk_fma_f32 v[4:5], v[6:7], 0.5, v[4:5] op_sel_hi:[1,0,1]
	v_lshlrev_b32_e32 v2, 16, v141
	v_and_b32_e32 v3, 0xffff0000, v141
	v_pk_fma_f32 v[2:3], v[8:9], 0.5, v[2:3] op_sel_hi:[1,0,1]
	v_cvt_pk_bf16_f32 v4, v4, v5
	v_cvt_pk_bf16_f32 v5, v2, v3
	v_and_b32_e32 v3, 0xffff0000, v4
	v_lshlrev_b32_e32 v2, 16, v4
	v_mul_f32_e32 v3, v3, v3
	global_store_dwordx2 v[36:37], v[4:5], off offset:80
	v_lshlrev_b32_e32 v4, 16, v5
	v_fmac_f32_e32 v3, v2, v2
	v_and_b32_e32 v5, 0xffff0000, v5
	v_fmac_f32_e32 v3, v4, v4
	v_fmac_f32_e32 v3, v5, v5
	v_add_f32_e32 v6, v18, v3
	s_waitcnt vmcnt(7)
	v_lshlrev_b32_e32 v4, 16, v142
	v_and_b32_e32 v5, 0xffff0000, v142
	v_pk_fma_f32 v[4:5], v[10:11], 0.5, v[4:5] op_sel_hi:[1,0,1]
	v_lshlrev_b32_e32 v2, 16, v143
	v_and_b32_e32 v3, 0xffff0000, v143
	v_pk_fma_f32 v[2:3], v[12:13], 0.5, v[2:3] op_sel_hi:[1,0,1]
	v_cvt_pk_bf16_f32 v4, v4, v5
	v_cvt_pk_bf16_f32 v5, v2, v3
	v_and_b32_e32 v3, 0xffff0000, v4
	v_lshlrev_b32_e32 v2, 16, v4
	v_mul_f32_e32 v3, v3, v3
	global_store_dwordx2 v[36:37], v[4:5], off offset:96
	v_lshlrev_b32_e32 v4, 16, v5
	v_fmac_f32_e32 v3, v2, v2
	v_and_b32_e32 v5, 0xffff0000, v5
	v_fmac_f32_e32 v3, v4, v4
	v_fmac_f32_e32 v3, v5, v5
	v_add_f32_e32 v4, v6, v3
	s_waitcnt vmcnt(7)
	v_lshlrev_b32_e32 v6, 16, v144
	v_and_b32_e32 v7, 0xffff0000, v144
	v_pk_fma_f32 v[6:7], v[14:15], 0.5, v[6:7] op_sel_hi:[1,0,1]
	v_lshlrev_b32_e32 v2, 16, v145
	v_and_b32_e32 v3, 0xffff0000, v145
	v_pk_fma_f32 v[2:3], v[16:17], 0.5, v[2:3] op_sel_hi:[1,0,1]
	v_cvt_pk_bf16_f32 v6, v6, v7
	v_cvt_pk_bf16_f32 v7, v2, v3
	v_and_b32_e32 v3, 0xffff0000, v6
	v_lshlrev_b32_e32 v2, 16, v6
	v_mul_f32_e32 v3, v3, v3
	v_lshlrev_b32_e32 v5, 16, v7
	v_fmac_f32_e32 v3, v2, v2
	global_store_dwordx2 v[36:37], v[6:7], off offset:112
	v_and_b32_e32 v6, 0xffff0000, v7
	v_fmac_f32_e32 v3, v5, v5
	v_fmac_f32_e32 v3, v6, v6
	v_add_f32_e32 v2, v4, v3
	ds_bpermute_b32 v0, v0, v2
	s_and_saveexec_b64 s[14:15], vcc
	s_cbranch_execz .LBB0_1287
	s_mul_i32 s16, s54, 0x20400
	s_mul_hi_i32 s17, s54, 0x20400
	s_add_u32 s16, s44, s16
	s_addc_u32 s17, s45, s17
	v_lshl_add_u64 v[4:5], v[34:35], 2, s[16:17]
	s_waitcnt lgkmcnt(0)
	v_add_f32_e32 v0, v2, v0
	global_store_dword v[4:5], v0, off
	s_branch .LBB0_1287
